# speedup vs baseline: 1.3412x; 1.0018x over previous
; #define LAS __attribute__((address_space(3)))
; __device__ __forceinline__ float logsigmoid_fast(float x) { return fminf(x, 0.f) - __logf(1.0f + __expf(-fabsf(x))); }
; template <int KIND, int MODE>
; __device__ __forceinline__ void scan_unit(Frame& F, int layer, int h, int vhalf, int grp) {
;     ...
;         for (int i = 0; i < 2; ++i) { const int e = tid + 512 * i; *(LAS u32x4*)(VS + (e >> 4) * VST + (e & 15) * 8) = pv[i]; }
;         if (KIND == 0) {
; #pragma unroll
;             for (int i = 0; i < 2; ++i) { const int c = tid + 512 * i, t = c >> 4, dc = (c & 15) * 8; const bf16_t* rp = proj + (size_t)(tb + t) * NP + h * 128 + dc;
;                 if (MODE == 1) *(LAS u32x4*)(QS + t * QST + dc) = pq[i];
;                 *(LAS u32x4*)(KS + t * QST + dc) = pk[i]; }
;             X[tid] = pl0; X[tid + 512] = pl1;
;             __syncthreads();
;             float bc[RPT]; float run = 0.f;
; #pragma unroll
;             for (int i = 0; i < RPT; ++i) { const LAS f32x4* lr = (const LAS f32x4*)(X + (tq * RPT + i) * 16); float z = bl;
; #pragma unroll
;                 for (int r = 0; r < 4; ++r) { const f32x4 l4 = lr[r]; z += l4[0] * wl[4 * r] + l4[1] * wl[4 * r + 1] + l4[2] * wl[4 * r + 2] + l4[3] * wl[4 * r + 3]; }
;                 run += logsigmoid_fast(z) * (1.0f / 16.0f); bc[i] = run; }
;             X[1024 + tq * 128 + d] = run;
.LBB0_424:
	v_add_u32_e32 v50, v92, v97
	ds_write_b128 v50, v[2:5]
	v_add_u32_e32 v50, v92, v98
	ds_write_b128 v50, v[6:9]
	v_add_u32_e32 v50, v0, v97
	ds_write_b128 v50, v[10:13] offset:33792
	v_add_u32_e32 v50, v0, v98
	ds_write_b128 v50, v[14:17] offset:33792
	ds_write2st64_b32 v93, v61, v60 offset1:8
	s_waitcnt lgkmcnt(0)
	s_barrier
	ds_read_b128 v[180:183], v94
	ds_read_b128 v[184:187], v94 offset:16
	ds_read_b128 v[188:191], v94 offset:32
	ds_read_b128 v[192:195], v94 offset:48
	ds_read_b128 v[196:199], v94 offset:64
	ds_read_b128 v[200:203], v94 offset:80
	ds_read_b128 v[204:207], v94 offset:96
	ds_read_b128 v[208:211], v94 offset:112
	s_waitcnt lgkmcnt(4)
	v_mul_f32_e32 v212, v76, v181
	v_fmac_f32_e32 v212, v75, v180
	v_fmac_f32_e32 v212, v77, v182
	v_fmac_f32_e32 v212, v78, v183
	v_add_f32_e32 v213, v91, v212
	v_mul_f32_e32 v212, v80, v185
	v_fmac_f32_e32 v212, v79, v184
	v_fmac_f32_e32 v212, v81, v186
	v_fmac_f32_e32 v212, v82, v187
	v_add_f32_e32 v213, v213, v212
	v_mul_f32_e32 v212, v84, v189
	v_fmac_f32_e32 v212, v83, v188
	v_fmac_f32_e32 v212, v85, v190
	v_fmac_f32_e32 v212, v86, v191
	v_add_f32_e32 v213, v213, v212
	v_mul_f32_e32 v212, v88, v193
	v_fmac_f32_e32 v212, v87, v192
	v_fmac_f32_e32 v212, v89, v194
	v_fmac_f32_e32 v212, v90, v195
	v_add_f32_e32 v213, v213, v212
	v_min_f32_e32 v214, 0, v213
	v_mul_f32_e64 v213, |v213|, s65
	v_exp_f32_e32 v213, v213
	s_nop 0
	v_add_f32_e32 v213, 1.0, v213
	v_log_f32_e32 v213, v213
	s_nop 0
	v_mul_f32_e32 v212, 0x3f317217, v213
	v_fma_f32 v212, v213, s75, -v212
	v_fmac_f32_e32 v212, 0x3377d1cf, v213
	v_fmac_f32_e32 v212, 0x3f317217, v213
	v_sub_f32_e32 v213, v214, v212
	v_fma_f32 v50, v213, s64, 0
	ds_read_b128 v[180:183], v94 offset:128
	ds_read_b128 v[184:187], v94 offset:144
	ds_read_b128 v[188:191], v94 offset:160
	ds_read_b128 v[192:195], v94 offset:176
	s_waitcnt lgkmcnt(4)
	v_mul_f32_e32 v212, v76, v197
	v_fmac_f32_e32 v212, v75, v196
	v_fmac_f32_e32 v212, v77, v198
	v_fmac_f32_e32 v212, v78, v199
	v_add_f32_e32 v213, v91, v212
	v_mul_f32_e32 v212, v80, v201
	v_fmac_f32_e32 v212, v79, v200
	v_fmac_f32_e32 v212, v81, v202
	v_fmac_f32_e32 v212, v82, v203
	v_add_f32_e32 v213, v213, v212
	v_mul_f32_e32 v212, v84, v205
	v_fmac_f32_e32 v212, v83, v204
	v_fmac_f32_e32 v212, v85, v206
	v_fmac_f32_e32 v212, v86, v207
	v_add_f32_e32 v213, v213, v212
	v_mul_f32_e32 v212, v88, v209
	v_fmac_f32_e32 v212, v87, v208
	v_fmac_f32_e32 v212, v89, v210
	v_fmac_f32_e32 v212, v90, v211
	v_add_f32_e32 v213, v213, v212
	v_min_f32_e32 v214, 0, v213
	v_mul_f32_e64 v213, |v213|, s65
	v_exp_f32_e32 v213, v213
	s_nop 0
	v_add_f32_e32 v213, 1.0, v213
	v_log_f32_e32 v213, v213
	s_nop 0
	v_mul_f32_e32 v212, 0x3f317217, v213
	v_fma_f32 v212, v213, s75, -v212
	v_fmac_f32_e32 v212, 0x3377d1cf, v213
	v_fmac_f32_e32 v212, 0x3f317217, v213
	v_sub_f32_e32 v213, v214, v212
	v_fmamk_f32 v51, v213, 0x3d800000, v50
	ds_read_b128 v[196:199], v94 offset:192
	ds_read_b128 v[200:203], v94 offset:208
	ds_read_b128 v[204:207], v94 offset:224
	ds_read_b128 v[208:211], v94 offset:240
	s_waitcnt lgkmcnt(4)
	v_mul_f32_e32 v212, v76, v181
	v_fmac_f32_e32 v212, v75, v180
	v_fmac_f32_e32 v212, v77, v182
	v_fmac_f32_e32 v212, v78, v183
	v_add_f32_e32 v213, v91, v212
	v_mul_f32_e32 v212, v80, v185
	v_fmac_f32_e32 v212, v79, v184
	v_fmac_f32_e32 v212, v81, v186
	v_fmac_f32_e32 v212, v82, v187
	v_add_f32_e32 v213, v213, v212
	v_mul_f32_e32 v212, v84, v189
	v_fmac_f32_e32 v212, v83, v188
	v_fmac_f32_e32 v212, v85, v190
	v_fmac_f32_e32 v212, v86, v191
	v_add_f32_e32 v213, v213, v212
	v_mul_f32_e32 v212, v88, v193
	v_fmac_f32_e32 v212, v87, v192
	v_fmac_f32_e32 v212, v89, v194
	v_fmac_f32_e32 v212, v90, v195
	v_add_f32_e32 v213, v213, v212
	v_min_f32_e32 v214, 0, v213
	v_mul_f32_e64 v213, |v213|, s65
	v_exp_f32_e32 v213, v213
	s_nop 0
	v_add_f32_e32 v213, 1.0, v213
	v_log_f32_e32 v213, v213
	s_nop 0
	v_mul_f32_e32 v212, 0x3f317217, v213
	v_fma_f32 v212, v213, s75, -v212
	v_fmac_f32_e32 v212, 0x3377d1cf, v213
	v_fmac_f32_e32 v212, 0x3f317217, v213
	v_sub_f32_e32 v213, v214, v212
	v_fmamk_f32 v52, v213, 0x3d800000, v51
	ds_read_b128 v[180:183], v94 offset:256
	ds_read_b128 v[184:187], v94 offset:272
	ds_read_b128 v[188:191], v94 offset:288
	ds_read_b128 v[192:195], v94 offset:304
	s_waitcnt lgkmcnt(4)
	v_mul_f32_e32 v212, v76, v197
	v_fmac_f32_e32 v212, v75, v196
	v_fmac_f32_e32 v212, v77, v198
	v_fmac_f32_e32 v212, v78, v199
	v_add_f32_e32 v213, v91, v212
	v_mul_f32_e32 v212, v80, v201
	v_fmac_f32_e32 v212, v79, v200
	v_fmac_f32_e32 v212, v81, v202
	v_fmac_f32_e32 v212, v82, v203
	v_add_f32_e32 v213, v213, v212
	v_mul_f32_e32 v212, v84, v205
	v_fmac_f32_e32 v212, v83, v204
	v_fmac_f32_e32 v212, v85, v206
	v_fmac_f32_e32 v212, v86, v207
	v_add_f32_e32 v213, v213, v212
	v_mul_f32_e32 v212, v88, v209
	v_fmac_f32_e32 v212, v87, v208
	v_fmac_f32_e32 v212, v89, v210
	v_fmac_f32_e32 v212, v90, v211
	v_add_f32_e32 v213, v213, v212
	v_min_f32_e32 v214, 0, v213
	v_mul_f32_e64 v213, |v213|, s65
	v_exp_f32_e32 v213, v213
	s_nop 0
	v_add_f32_e32 v213, 1.0, v213
	v_log_f32_e32 v213, v213
	s_nop 0
	v_mul_f32_e32 v212, 0x3f317217, v213
	v_fma_f32 v212, v213, s75, -v212
	v_fmac_f32_e32 v212, 0x3377d1cf, v213
	v_fmac_f32_e32 v212, 0x3f317217, v213
	v_sub_f32_e32 v213, v214, v212
	v_fmamk_f32 v53, v213, 0x3d800000, v52
	ds_read_b128 v[196:199], v94 offset:320
	ds_read_b128 v[200:203], v94 offset:336
	ds_read_b128 v[204:207], v94 offset:352
	ds_read_b128 v[208:211], v94 offset:368
	s_waitcnt lgkmcnt(4)
; #define LAS __attribute__((address_space(3)))
; __device__ __forceinline__ float logsigmoid_fast(float x) { return fminf(x, 0.f) - __logf(1.0f + __expf(-fabsf(x))); }
; template <int KIND, int MODE>
; __device__ __forceinline__ void scan_unit(Frame& F, int layer, int h, int vhalf, int grp) {
;     ...
;             for (int i = 0; i < RPT; ++i) { const LAS f32x4* lr = (const LAS f32x4*)(X + (tq * RPT + i) * 16); float z = bl;
; #pragma unroll
;                 for (int r = 0; r < 4; ++r) { const f32x4 l4 = lr[r]; z += l4[0] * wl[4 * r] + l4[1] * wl[4 * r + 1] + l4[2] * wl[4 * r + 2] + l4[3] * wl[4 * r + 3]; }
;                 run += logsigmoid_fast(z) * (1.0f / 16.0f); bc[i] = run; }
	v_mul_f32_e32 v212, v76, v181
	v_fmac_f32_e32 v212, v75, v180
	v_fmac_f32_e32 v212, v77, v182
	v_fmac_f32_e32 v212, v78, v183
	v_add_f32_e32 v213, v91, v212
	v_mul_f32_e32 v212, v80, v185
	v_fmac_f32_e32 v212, v79, v184
	v_fmac_f32_e32 v212, v81, v186
	v_fmac_f32_e32 v212, v82, v187
	v_add_f32_e32 v213, v213, v212
	v_mul_f32_e32 v212, v84, v189
	v_fmac_f32_e32 v212, v83, v188
	v_fmac_f32_e32 v212, v85, v190
	v_fmac_f32_e32 v212, v86, v191
	v_add_f32_e32 v213, v213, v212
	v_mul_f32_e32 v212, v88, v193
	v_fmac_f32_e32 v212, v87, v192
	v_fmac_f32_e32 v212, v89, v194
	v_fmac_f32_e32 v212, v90, v195
	v_add_f32_e32 v213, v213, v212
	v_min_f32_e32 v214, 0, v213
	v_mul_f32_e64 v213, |v213|, s65
	v_exp_f32_e32 v213, v213
	s_nop 0
	v_add_f32_e32 v213, 1.0, v213
	v_log_f32_e32 v213, v213
	s_nop 0
	v_mul_f32_e32 v212, 0x3f317217, v213
	v_fma_f32 v212, v213, s75, -v212
	v_fmac_f32_e32 v212, 0x3377d1cf, v213
	v_fmac_f32_e32 v212, 0x3f317217, v213
	v_sub_f32_e32 v213, v214, v212
	v_fmamk_f32 v54, v213, 0x3d800000, v53
	ds_read_b128 v[180:183], v94 offset:384
	ds_read_b128 v[184:187], v94 offset:400
	ds_read_b128 v[188:191], v94 offset:416
	ds_read_b128 v[192:195], v94 offset:432
	s_waitcnt lgkmcnt(4)
	v_mul_f32_e32 v212, v76, v197
	v_fmac_f32_e32 v212, v75, v196
	v_fmac_f32_e32 v212, v77, v198
	v_fmac_f32_e32 v212, v78, v199
	v_add_f32_e32 v213, v91, v212
	v_mul_f32_e32 v212, v80, v201
	v_fmac_f32_e32 v212, v79, v200
	v_fmac_f32_e32 v212, v81, v202
	v_fmac_f32_e32 v212, v82, v203
	v_add_f32_e32 v213, v213, v212
	v_mul_f32_e32 v212, v84, v205
	v_fmac_f32_e32 v212, v83, v204
	v_fmac_f32_e32 v212, v85, v206
	v_fmac_f32_e32 v212, v86, v207
	v_add_f32_e32 v213, v213, v212
	v_mul_f32_e32 v212, v88, v209
	v_fmac_f32_e32 v212, v87, v208
	v_fmac_f32_e32 v212, v89, v210
	v_fmac_f32_e32 v212, v90, v211
	v_add_f32_e32 v213, v213, v212
	v_min_f32_e32 v214, 0, v213
	v_mul_f32_e64 v213, |v213|, s65
	v_exp_f32_e32 v213, v213
	s_nop 0
	v_add_f32_e32 v213, 1.0, v213
	v_log_f32_e32 v213, v213
	s_nop 0
	v_mul_f32_e32 v212, 0x3f317217, v213
	v_fma_f32 v212, v213, s75, -v212
	v_fmac_f32_e32 v212, 0x3377d1cf, v213
	v_fmac_f32_e32 v212, 0x3f317217, v213
	v_sub_f32_e32 v213, v214, v212
	v_fmamk_f32 v55, v213, 0x3d800000, v54
	ds_read_b128 v[196:199], v94 offset:448
	ds_read_b128 v[200:203], v94 offset:464
	ds_read_b128 v[204:207], v94 offset:480
	ds_read_b128 v[208:211], v94 offset:496
	s_waitcnt lgkmcnt(4)
	v_mul_f32_e32 v212, v76, v181
	v_fmac_f32_e32 v212, v75, v180
	v_fmac_f32_e32 v212, v77, v182
	v_fmac_f32_e32 v212, v78, v183
	v_add_f32_e32 v213, v91, v212
	v_mul_f32_e32 v212, v80, v185
	v_fmac_f32_e32 v212, v79, v184
	v_fmac_f32_e32 v212, v81, v186
	v_fmac_f32_e32 v212, v82, v187
	v_add_f32_e32 v213, v213, v212
	v_mul_f32_e32 v212, v84, v189
	v_fmac_f32_e32 v212, v83, v188
	v_fmac_f32_e32 v212, v85, v190
	v_fmac_f32_e32 v212, v86, v191
	v_add_f32_e32 v213, v213, v212
	v_mul_f32_e32 v212, v88, v193
	v_fmac_f32_e32 v212, v87, v192
	v_fmac_f32_e32 v212, v89, v194
	v_fmac_f32_e32 v212, v90, v195
	v_add_f32_e32 v213, v213, v212
	v_min_f32_e32 v214, 0, v213
	v_mul_f32_e64 v213, |v213|, s65
	v_exp_f32_e32 v213, v213
	s_nop 0
	v_add_f32_e32 v213, 1.0, v213
	v_log_f32_e32 v213, v213
	s_nop 0
	v_mul_f32_e32 v212, 0x3f317217, v213
	v_fma_f32 v212, v213, s75, -v212
	v_fmac_f32_e32 v212, 0x3377d1cf, v213
	v_fmac_f32_e32 v212, 0x3f317217, v213
	v_sub_f32_e32 v213, v214, v212
	v_fmamk_f32 v56, v213, 0x3d800000, v55
	ds_read_b128 v[180:183], v94 offset:512
	ds_read_b128 v[184:187], v94 offset:528
	ds_read_b128 v[188:191], v94 offset:544
	ds_read_b128 v[192:195], v94 offset:560
	s_waitcnt lgkmcnt(4)
	v_mul_f32_e32 v212, v76, v197
	v_fmac_f32_e32 v212, v75, v196
	v_fmac_f32_e32 v212, v77, v198
	v_fmac_f32_e32 v212, v78, v199
	v_add_f32_e32 v213, v91, v212
	v_mul_f32_e32 v212, v80, v201
	v_fmac_f32_e32 v212, v79, v200
	v_fmac_f32_e32 v212, v81, v202
	v_fmac_f32_e32 v212, v82, v203
	v_add_f32_e32 v213, v213, v212
	v_mul_f32_e32 v212, v84, v205
	v_fmac_f32_e32 v212, v83, v204
	v_fmac_f32_e32 v212, v85, v206
	v_fmac_f32_e32 v212, v86, v207
	v_add_f32_e32 v213, v213, v212
	v_mul_f32_e32 v212, v88, v209
	v_fmac_f32_e32 v212, v87, v208
	v_fmac_f32_e32 v212, v89, v210
	v_fmac_f32_e32 v212, v90, v211
	v_add_f32_e32 v213, v213, v212
	v_min_f32_e32 v214, 0, v213
	v_mul_f32_e64 v213, |v213|, s65
	v_exp_f32_e32 v213, v213
	s_nop 0
	v_add_f32_e32 v213, 1.0, v213
	v_log_f32_e32 v213, v213
	s_nop 0
	v_mul_f32_e32 v212, 0x3f317217, v213
	v_fma_f32 v212, v213, s75, -v212
	v_fmac_f32_e32 v212, 0x3377d1cf, v213
	v_fmac_f32_e32 v212, 0x3f317217, v213
	v_sub_f32_e32 v213, v214, v212
	v_fmamk_f32 v124, v213, 0x3d800000, v56
	ds_read_b128 v[196:199], v94 offset:576
	ds_read_b128 v[200:203], v94 offset:592
	ds_read_b128 v[204:207], v94 offset:608
	ds_read_b128 v[208:211], v94 offset:624
	s_waitcnt lgkmcnt(4)
	v_mul_f32_e32 v212, v76, v181
	v_fmac_f32_e32 v212, v75, v180
	v_fmac_f32_e32 v212, v77, v182
	v_fmac_f32_e32 v212, v78, v183
	v_add_f32_e32 v213, v91, v212
	v_mul_f32_e32 v212, v80, v185
	v_fmac_f32_e32 v212, v79, v184
	v_fmac_f32_e32 v212, v81, v186
	v_fmac_f32_e32 v212, v82, v187
	v_add_f32_e32 v213, v213, v212
	v_mul_f32_e32 v212, v84, v189
	v_fmac_f32_e32 v212, v83, v188
	v_fmac_f32_e32 v212, v85, v190
	v_fmac_f32_e32 v212, v86, v191
	v_add_f32_e32 v213, v213, v212
	v_mul_f32_e32 v212, v88, v193
	v_fmac_f32_e32 v212, v87, v192
	v_fmac_f32_e32 v212, v89, v194
	v_fmac_f32_e32 v212, v90, v195
	v_add_f32_e32 v213, v213, v212
	v_min_f32_e32 v214, 0, v213
	v_mul_f32_e64 v213, |v213|, s65
	v_exp_f32_e32 v213, v213
	s_nop 0
	v_add_f32_e32 v213, 1.0, v213
	v_log_f32_e32 v213, v213
	s_nop 0
	v_mul_f32_e32 v212, 0x3f317217, v213
	v_fma_f32 v212, v213, s75, -v212
	v_fmac_f32_e32 v212, 0x3377d1cf, v213
	v_fmac_f32_e32 v212, 0x3f317217, v213
	v_sub_f32_e32 v213, v214, v212
	v_fmamk_f32 v57, v213, 0x3d800000, v124
	ds_read_b128 v[180:183], v94 offset:640
	ds_read_b128 v[184:187], v94 offset:656
	ds_read_b128 v[188:191], v94 offset:672
	ds_read_b128 v[192:195], v94 offset:688
	s_waitcnt lgkmcnt(4)
; #define LAS __attribute__((address_space(3)))
; __device__ __forceinline__ float logsigmoid_fast(float x) { return fminf(x, 0.f) - __logf(1.0f + __expf(-fabsf(x))); }
; template <int KIND, int MODE>
; __device__ __forceinline__ void scan_unit(Frame& F, int layer, int h, int vhalf, int grp) {
;     ...
;             for (int i = 0; i < RPT; ++i) { const LAS f32x4* lr = (const LAS f32x4*)(X + (tq * RPT + i) * 16); float z = bl;
; #pragma unroll
;                 for (int r = 0; r < 4; ++r) { const f32x4 l4 = lr[r]; z += l4[0] * wl[4 * r] + l4[1] * wl[4 * r + 1] + l4[2] * wl[4 * r + 2] + l4[3] * wl[4 * r + 3]; }
;                 run += logsigmoid_fast(z) * (1.0f / 16.0f); bc[i] = run; }
	v_mul_f32_e32 v212, v76, v197
	v_fmac_f32_e32 v212, v75, v196
	v_fmac_f32_e32 v212, v77, v198
	v_fmac_f32_e32 v212, v78, v199
	v_add_f32_e32 v213, v91, v212
	v_mul_f32_e32 v212, v80, v201
	v_fmac_f32_e32 v212, v79, v200
	v_fmac_f32_e32 v212, v81, v202
	v_fmac_f32_e32 v212, v82, v203
	v_add_f32_e32 v213, v213, v212
	v_mul_f32_e32 v212, v84, v205
	v_fmac_f32_e32 v212, v83, v204
	v_fmac_f32_e32 v212, v85, v206
	v_fmac_f32_e32 v212, v86, v207
	v_add_f32_e32 v213, v213, v212
	v_mul_f32_e32 v212, v88, v209
	v_fmac_f32_e32 v212, v87, v208
	v_fmac_f32_e32 v212, v89, v210
	v_fmac_f32_e32 v212, v90, v211
	v_add_f32_e32 v213, v213, v212
	v_min_f32_e32 v214, 0, v213
	v_mul_f32_e64 v213, |v213|, s65
	v_exp_f32_e32 v213, v213
	s_nop 0
	v_add_f32_e32 v213, 1.0, v213
	v_log_f32_e32 v213, v213
	s_nop 0
	v_mul_f32_e32 v212, 0x3f317217, v213
	v_fma_f32 v212, v213, s75, -v212
	v_fmac_f32_e32 v212, 0x3377d1cf, v213
	v_fmac_f32_e32 v212, 0x3f317217, v213
	v_sub_f32_e32 v213, v214, v212
	v_fmamk_f32 v125, v213, 0x3d800000, v57
	ds_read_b128 v[196:199], v94 offset:704
	ds_read_b128 v[200:203], v94 offset:720
	ds_read_b128 v[204:207], v94 offset:736
	ds_read_b128 v[208:211], v94 offset:752
	s_waitcnt lgkmcnt(4)
	v_mul_f32_e32 v212, v76, v181
	v_fmac_f32_e32 v212, v75, v180
	v_fmac_f32_e32 v212, v77, v182
	v_fmac_f32_e32 v212, v78, v183
	v_add_f32_e32 v213, v91, v212
	v_mul_f32_e32 v212, v80, v185
	v_fmac_f32_e32 v212, v79, v184
	v_fmac_f32_e32 v212, v81, v186
	v_fmac_f32_e32 v212, v82, v187
	v_add_f32_e32 v213, v213, v212
	v_mul_f32_e32 v212, v84, v189
	v_fmac_f32_e32 v212, v83, v188
	v_fmac_f32_e32 v212, v85, v190
	v_fmac_f32_e32 v212, v86, v191
	v_add_f32_e32 v213, v213, v212
	v_mul_f32_e32 v212, v88, v193
	v_fmac_f32_e32 v212, v87, v192
	v_fmac_f32_e32 v212, v89, v194
	v_fmac_f32_e32 v212, v90, v195
	v_add_f32_e32 v213, v213, v212
	v_min_f32_e32 v214, 0, v213
	v_mul_f32_e64 v213, |v213|, s65
	v_exp_f32_e32 v213, v213
	s_nop 0
	v_add_f32_e32 v213, 1.0, v213
	v_log_f32_e32 v213, v213
	s_nop 0
	v_mul_f32_e32 v212, 0x3f317217, v213
	v_fma_f32 v212, v213, s75, -v212
	v_fmac_f32_e32 v212, 0x3377d1cf, v213
	v_fmac_f32_e32 v212, 0x3f317217, v213
	v_sub_f32_e32 v213, v214, v212
	v_fmamk_f32 v126, v213, 0x3d800000, v125
	ds_read_b128 v[180:183], v94 offset:768
	ds_read_b128 v[184:187], v94 offset:784
	ds_read_b128 v[188:191], v94 offset:800
	ds_read_b128 v[192:195], v94 offset:816
	s_waitcnt lgkmcnt(4)
	v_mul_f32_e32 v212, v76, v197
	v_fmac_f32_e32 v212, v75, v196
	v_fmac_f32_e32 v212, v77, v198
	v_fmac_f32_e32 v212, v78, v199
	v_add_f32_e32 v213, v91, v212
	v_mul_f32_e32 v212, v80, v201
	v_fmac_f32_e32 v212, v79, v200
	v_fmac_f32_e32 v212, v81, v202
	v_fmac_f32_e32 v212, v82, v203
	v_add_f32_e32 v213, v213, v212
	v_mul_f32_e32 v212, v84, v205
	v_fmac_f32_e32 v212, v83, v204
	v_fmac_f32_e32 v212, v85, v206
	v_fmac_f32_e32 v212, v86, v207
	v_add_f32_e32 v213, v213, v212
	v_mul_f32_e32 v212, v88, v209
	v_fmac_f32_e32 v212, v87, v208
	v_fmac_f32_e32 v212, v89, v210
	v_fmac_f32_e32 v212, v90, v211
	v_add_f32_e32 v213, v213, v212
	v_min_f32_e32 v214, 0, v213
	v_mul_f32_e64 v213, |v213|, s65
	v_exp_f32_e32 v213, v213
	s_nop 0
	v_add_f32_e32 v213, 1.0, v213
	v_log_f32_e32 v213, v213
	s_nop 0
	v_mul_f32_e32 v212, 0x3f317217, v213
	v_fma_f32 v212, v213, s75, -v212
	v_fmac_f32_e32 v212, 0x3377d1cf, v213
	v_fmac_f32_e32 v212, 0x3f317217, v213
	v_sub_f32_e32 v213, v214, v212
	v_fmamk_f32 v127, v213, 0x3d800000, v126
	ds_read_b128 v[196:199], v94 offset:832
	ds_read_b128 v[200:203], v94 offset:848
	ds_read_b128 v[204:207], v94 offset:864
	ds_read_b128 v[208:211], v94 offset:880
	s_waitcnt lgkmcnt(4)
	v_mul_f32_e32 v212, v76, v181
	v_fmac_f32_e32 v212, v75, v180
	v_fmac_f32_e32 v212, v77, v182
	v_fmac_f32_e32 v212, v78, v183
	v_add_f32_e32 v213, v91, v212
	v_mul_f32_e32 v212, v80, v185
	v_fmac_f32_e32 v212, v79, v184
	v_fmac_f32_e32 v212, v81, v186
	v_fmac_f32_e32 v212, v82, v187
	v_add_f32_e32 v213, v213, v212
	v_mul_f32_e32 v212, v84, v189
	v_fmac_f32_e32 v212, v83, v188
	v_fmac_f32_e32 v212, v85, v190
	v_fmac_f32_e32 v212, v86, v191
	v_add_f32_e32 v213, v213, v212
	v_mul_f32_e32 v212, v88, v193
	v_fmac_f32_e32 v212, v87, v192
	v_fmac_f32_e32 v212, v89, v194
	v_fmac_f32_e32 v212, v90, v195
	v_add_f32_e32 v213, v213, v212
	v_min_f32_e32 v214, 0, v213
	v_mul_f32_e64 v213, |v213|, s65
	v_exp_f32_e32 v213, v213
	s_nop 0
	v_add_f32_e32 v213, 1.0, v213
	v_log_f32_e32 v213, v213
	s_nop 0
	v_mul_f32_e32 v212, 0x3f317217, v213
	v_fma_f32 v212, v213, s75, -v212
	v_fmac_f32_e32 v212, 0x3377d1cf, v213
	v_fmac_f32_e32 v212, 0x3f317217, v213
	v_sub_f32_e32 v213, v214, v212
	v_fmamk_f32 v128, v213, 0x3d800000, v127
	ds_read_b128 v[180:183], v94 offset:896
	ds_read_b128 v[184:187], v94 offset:912
	ds_read_b128 v[188:191], v94 offset:928
	ds_read_b128 v[192:195], v94 offset:944
	s_waitcnt lgkmcnt(4)
	v_mul_f32_e32 v212, v76, v197
	v_fmac_f32_e32 v212, v75, v196
	v_fmac_f32_e32 v212, v77, v198
	v_fmac_f32_e32 v212, v78, v199
	v_add_f32_e32 v213, v91, v212
	v_mul_f32_e32 v212, v80, v201
	v_fmac_f32_e32 v212, v79, v200
	v_fmac_f32_e32 v212, v81, v202
	v_fmac_f32_e32 v212, v82, v203
	v_add_f32_e32 v213, v213, v212
	v_mul_f32_e32 v212, v84, v205
	v_fmac_f32_e32 v212, v83, v204
	v_fmac_f32_e32 v212, v85, v206
	v_fmac_f32_e32 v212, v86, v207
	v_add_f32_e32 v213, v213, v212
	v_mul_f32_e32 v212, v88, v209
	v_fmac_f32_e32 v212, v87, v208
	v_fmac_f32_e32 v212, v89, v210
	v_fmac_f32_e32 v212, v90, v211
	v_add_f32_e32 v213, v213, v212
	v_min_f32_e32 v214, 0, v213
	v_mul_f32_e64 v213, |v213|, s65
	v_exp_f32_e32 v213, v213
	s_nop 0
	v_add_f32_e32 v213, 1.0, v213
	v_log_f32_e32 v213, v213
	s_nop 0
	v_mul_f32_e32 v212, 0x3f317217, v213
	v_fma_f32 v212, v213, s75, -v212
	v_fmac_f32_e32 v212, 0x3377d1cf, v213
	v_fmac_f32_e32 v212, 0x3f317217, v213
	v_sub_f32_e32 v213, v214, v212
	v_fmamk_f32 v129, v213, 0x3d800000, v128
	ds_read_b128 v[196:199], v94 offset:960
	ds_read_b128 v[200:203], v94 offset:976
	ds_read_b128 v[204:207], v94 offset:992
	ds_read_b128 v[208:211], v94 offset:1008
	s_waitcnt lgkmcnt(4)
; #define LAS __attribute__((address_space(3)))
; __device__ __forceinline__ float logsigmoid_fast(float x) { return fminf(x, 0.f) - __logf(1.0f + __expf(-fabsf(x))); }
; template <int KIND, int MODE>
; __device__ __forceinline__ void scan_unit(Frame& F, int layer, int h, int vhalf, int grp) {
;     ...
;             for (int i = 0; i < RPT; ++i) { const LAS f32x4* lr = (const LAS f32x4*)(X + (tq * RPT + i) * 16); float z = bl;
; #pragma unroll
;                 for (int r = 0; r < 4; ++r) { const f32x4 l4 = lr[r]; z += l4[0] * wl[4 * r] + l4[1] * wl[4 * r + 1] + l4[2] * wl[4 * r + 2] + l4[3] * wl[4 * r + 3]; }
;                 run += logsigmoid_fast(z) * (1.0f / 16.0f); bc[i] = run; }
;             X[1024 + tq * 128 + d] = run;
	v_mul_f32_e32 v212, v76, v181
	v_fmac_f32_e32 v212, v75, v180
	v_fmac_f32_e32 v212, v77, v182
	v_fmac_f32_e32 v212, v78, v183
	v_add_f32_e32 v213, v91, v212
	v_mul_f32_e32 v212, v80, v185
	v_fmac_f32_e32 v212, v79, v184
	v_fmac_f32_e32 v212, v81, v186
	v_fmac_f32_e32 v212, v82, v187
	v_add_f32_e32 v213, v213, v212
	v_mul_f32_e32 v212, v84, v189
	v_fmac_f32_e32 v212, v83, v188
	v_fmac_f32_e32 v212, v85, v190
	v_fmac_f32_e32 v212, v86, v191
	v_add_f32_e32 v213, v213, v212
	v_mul_f32_e32 v212, v88, v193
	v_fmac_f32_e32 v212, v87, v192
	v_fmac_f32_e32 v212, v89, v194
	v_fmac_f32_e32 v212, v90, v195
	v_add_f32_e32 v213, v213, v212
	v_min_f32_e32 v214, 0, v213
	v_mul_f32_e64 v213, |v213|, s65
	v_exp_f32_e32 v213, v213
	s_nop 0
	v_add_f32_e32 v213, 1.0, v213
	v_log_f32_e32 v213, v213
	s_nop 0
	v_mul_f32_e32 v212, 0x3f317217, v213
	v_fma_f32 v212, v213, s75, -v212
	v_fmac_f32_e32 v212, 0x3377d1cf, v213
	v_fmac_f32_e32 v212, 0x3f317217, v213
	v_sub_f32_e32 v213, v214, v212
	v_fmamk_f32 v131, v213, 0x3d800000, v129
	s_waitcnt lgkmcnt(0)
	v_mul_f32_e32 v212, v76, v197
	v_fmac_f32_e32 v212, v75, v196
	v_fmac_f32_e32 v212, v77, v198
	v_fmac_f32_e32 v212, v78, v199
	v_add_f32_e32 v213, v91, v212
	v_mul_f32_e32 v212, v80, v201
	v_fmac_f32_e32 v212, v79, v200
	v_fmac_f32_e32 v212, v81, v202
	v_fmac_f32_e32 v212, v82, v203
	v_add_f32_e32 v213, v213, v212
	v_mul_f32_e32 v212, v84, v205
	v_fmac_f32_e32 v212, v83, v204
	v_fmac_f32_e32 v212, v85, v206
	v_fmac_f32_e32 v212, v86, v207
	v_add_f32_e32 v213, v213, v212
	v_mul_f32_e32 v212, v88, v209
	v_fmac_f32_e32 v212, v87, v208
	v_fmac_f32_e32 v212, v89, v210
	v_fmac_f32_e32 v212, v90, v211
	v_add_f32_e32 v213, v213, v212
	v_min_f32_e32 v214, 0, v213
	v_mul_f32_e64 v213, |v213|, s65
	v_exp_f32_e32 v213, v213
	s_nop 0
	v_add_f32_e32 v213, 1.0, v213
	v_log_f32_e32 v213, v213
	s_nop 0
	v_mul_f32_e32 v212, 0x3f317217, v213
	v_fma_f32 v212, v213, s75, -v212
	v_fmac_f32_e32 v212, 0x3377d1cf, v213
	v_fmac_f32_e32 v212, 0x3f317217, v213
	v_sub_f32_e32 v213, v214, v212
	v_fmamk_f32 v132, v213, 0x3d800000, v131
	ds_write_b32 v96, v132 offset:4096
	s_waitcnt lgkmcnt(0)
	s_barrier
; __device__ __forceinline__ unsigned pk2hw(float lo, float hi) { unsigned r; asm("s_nop 1\n\tv_cvt_pk_bf16_f32 %0, %1, %2" : "=v"(r) : "v"(lo), "v"(hi)); return r; }
; template <int KIND, int MODE>
; __device__ __forceinline__ void scan_unit(Frame& F, int layer, int h, int vhalf, int grp) {
;     ...
;             float pre = 0.f, tot = 0.f;
; #pragma unroll
;             for (int qq = 0; qq < NTQ; ++qq) { const float v = X[1024 + qq * 128 + d]; tot += v; if (qq < tq) pre += v; }
;             const float etot = __expf(tot);
;             if (tq == 0) { X[1536 + d] = etot; gtot += tot; }
; #pragma unroll
;             for (int i = 0; i < RPT; ++i) { const int t = tq * RPT + i; const float bcv = bc[i] + pre;
;                 const float kv = bf2f(KS[t * QST + d]); const float eb = __expf(bcv), ib = __builtin_amdgcn_rcpf(eb);
;                 if (MODE == 1) { const float qv = bf2f(QS[t * QST + d]); const unsigned w0 = pk2hw(qv * 0.08838834764831845f * eb, kv * ib); QS[t * QST + d] = (unsigned short)w0; KS[t * QST + d] = (unsigned short)(w0 >> 16); }
;                 K2[t * QST + d] = (unsigned short)pk2hw(kv * (etot * ib), 0.f); }
;             if (PREF && ch + 1 < (grp + 1) * GC) SCAN_LOAD(tb + 64);
	ds_read_b32 v130, v99
	ds_read_b32 v134, v101
	ds_read_b32 v135, v102
	ds_read_b32 v136, v103
	s_waitcnt lgkmcnt(3)
	v_add_f32_e32 v133, 0, v130
	s_waitcnt lgkmcnt(2)
	v_add_f32_e32 v130, v133, v134
	s_waitcnt lgkmcnt(1)
	v_add_f32_e32 v130, v130, v135
	s_waitcnt lgkmcnt(0)
	v_add_f32_e32 v137, v130, v136
	v_mul_f32_e32 v130, 0x3fb8aa3b, v137
	v_exp_f32_e32 v130, v130
	s_and_saveexec_b64 s[0:1], vcc
	v_add_f32_e32 v100, v100, v137
	ds_write_b32 v95, v130 offset:6144
	s_or_b64 exec, exec, s[0:1]
	v_cndmask_b32_e64 v133, 0, v133, s[8:9]
	v_add_f32_e32 v134, v134, v133
	v_cndmask_b32_e64 v133, v133, v134, s[10:11]
	v_add_f32_e32 v134, v135, v133
	v_cndmask_b32_e64 v133, v133, v134, s[12:13]
	v_add_f32_e32 v134, v136, v133
	v_cndmask_b32_e64 v133, v133, v134, s[14:15]
	v_add_f32_e32 v50, v50, v133
	v_mul_f32_e32 v50, 0x3fb8aa3b, v50
	v_exp_f32_e32 v50, v50
	ds_read_u16 v134, v104 offset:33792
	s_cmp_ge_i32 s24, s23
	v_rcp_f32_e32 v50, v50
	s_waitcnt lgkmcnt(0)
	v_lshlrev_b32_e32 v134, 16, v134
	v_mul_f32_e32 v50, v130, v50
	v_mul_f32_e32 v50, v50, v134
	s_nop 1
	v_cvt_pk_bf16_f32 v50, v50, v1
	ds_write_b16 v105, v50
	v_add_f32_e32 v50, v51, v133
	v_mul_f32_e32 v50, 0x3fb8aa3b, v50
	v_exp_f32_e32 v50, v50
	ds_read_u16 v51, v104 offset:34064
	v_rcp_f32_e32 v50, v50
	s_waitcnt lgkmcnt(0)
	v_lshlrev_b32_e32 v51, 16, v51
	v_mul_f32_e32 v50, v130, v50
	v_mul_f32_e32 v50, v50, v51
	s_nop 1
	v_cvt_pk_bf16_f32 v50, v50, v1
	ds_write_b16 v106, v50
	v_add_f32_e32 v50, v52, v133
	v_mul_f32_e32 v50, 0x3fb8aa3b, v50
	v_exp_f32_e32 v50, v50
	ds_read_u16 v51, v104 offset:34336
	v_rcp_f32_e32 v50, v50
	s_waitcnt lgkmcnt(0)
	v_lshlrev_b32_e32 v51, 16, v51
	v_mul_f32_e32 v50, v130, v50
	v_mul_f32_e32 v50, v50, v51
	s_nop 1
	v_cvt_pk_bf16_f32 v50, v50, v1
	ds_write_b16 v107, v50
	v_add_f32_e32 v50, v53, v133
	v_mul_f32_e32 v50, 0x3fb8aa3b, v50
	v_exp_f32_e32 v50, v50
	ds_read_u16 v51, v104 offset:34608
	v_rcp_f32_e32 v50, v50
	s_waitcnt lgkmcnt(0)
	v_lshlrev_b32_e32 v51, 16, v51
	v_mul_f32_e32 v50, v130, v50
	v_mul_f32_e32 v50, v50, v51
	s_nop 1
	v_cvt_pk_bf16_f32 v50, v50, v1
	ds_write_b16 v108, v50
	v_add_f32_e32 v50, v54, v133
	v_mul_f32_e32 v50, 0x3fb8aa3b, v50
	v_exp_f32_e32 v50, v50
	ds_read_u16 v51, v104 offset:34880
	v_rcp_f32_e32 v50, v50
	s_waitcnt lgkmcnt(0)
	v_lshlrev_b32_e32 v51, 16, v51
	v_mul_f32_e32 v50, v130, v50
	v_mul_f32_e32 v50, v50, v51
	s_nop 1
	v_cvt_pk_bf16_f32 v50, v50, v1
	ds_write_b16 v109, v50
	v_add_f32_e32 v50, v55, v133
	v_mul_f32_e32 v50, 0x3fb8aa3b, v50
	v_exp_f32_e32 v50, v50
	ds_read_u16 v51, v104 offset:35152
	v_rcp_f32_e32 v50, v50
	s_waitcnt lgkmcnt(0)
	v_lshlrev_b32_e32 v51, 16, v51
	v_mul_f32_e32 v50, v130, v50
	v_mul_f32_e32 v50, v50, v51
	s_nop 1
	v_cvt_pk_bf16_f32 v50, v50, v1
	ds_write_b16 v110, v50
	v_add_f32_e32 v50, v56, v133
	v_mul_f32_e32 v50, 0x3fb8aa3b, v50
	v_exp_f32_e32 v50, v50
	ds_read_u16 v51, v104 offset:35424
	v_rcp_f32_e32 v50, v50
	s_waitcnt lgkmcnt(0)
	v_lshlrev_b32_e32 v51, 16, v51
	v_mul_f32_e32 v50, v130, v50
	v_mul_f32_e32 v50, v50, v51
	s_nop 1
	v_cvt_pk_bf16_f32 v50, v50, v1
	ds_write_b16 v111, v50
	v_add_f32_e32 v50, v124, v133
	v_mul_f32_e32 v50, 0x3fb8aa3b, v50
	v_exp_f32_e32 v50, v50
	ds_read_u16 v51, v104 offset:35696
	v_rcp_f32_e32 v50, v50
	s_waitcnt lgkmcnt(0)
	v_lshlrev_b32_e32 v51, 16, v51
	v_mul_f32_e32 v50, v130, v50
	v_mul_f32_e32 v50, v50, v51
	s_nop 1
	v_cvt_pk_bf16_f32 v50, v50, v1
	ds_write_b16 v112, v50
	v_add_f32_e32 v50, v57, v133
	v_mul_f32_e32 v50, 0x3fb8aa3b, v50
	v_exp_f32_e32 v50, v50
	ds_read_u16 v51, v104 offset:35968
	v_rcp_f32_e32 v50, v50
	s_waitcnt lgkmcnt(0)
	v_lshlrev_b32_e32 v51, 16, v51
	v_mul_f32_e32 v50, v130, v50
	v_mul_f32_e32 v50, v50, v51
	s_nop 1
	v_cvt_pk_bf16_f32 v50, v50, v1
	ds_write_b16 v113, v50
	v_add_f32_e32 v50, v125, v133
	v_mul_f32_e32 v50, 0x3fb8aa3b, v50
	v_exp_f32_e32 v50, v50
	ds_read_u16 v51, v104 offset:36240
	v_rcp_f32_e32 v50, v50
	s_waitcnt lgkmcnt(0)
	v_lshlrev_b32_e32 v51, 16, v51
	v_mul_f32_e32 v50, v130, v50
	v_mul_f32_e32 v50, v50, v51
	s_nop 1
	v_cvt_pk_bf16_f32 v50, v50, v1
	ds_write_b16 v114, v50
	v_add_f32_e32 v50, v126, v133
	v_mul_f32_e32 v50, 0x3fb8aa3b, v50
	v_exp_f32_e32 v50, v50
	ds_read_u16 v51, v104 offset:36512
	v_rcp_f32_e32 v50, v50
	s_waitcnt lgkmcnt(0)
	v_lshlrev_b32_e32 v51, 16, v51
	v_mul_f32_e32 v50, v130, v50
	v_mul_f32_e32 v50, v50, v51
	s_nop 1
	v_cvt_pk_bf16_f32 v50, v50, v1
	ds_write_b16 v115, v50
	v_add_f32_e32 v50, v127, v133
	v_mul_f32_e32 v50, 0x3fb8aa3b, v50
	v_exp_f32_e32 v50, v50
	ds_read_u16 v51, v104 offset:36784
	v_rcp_f32_e32 v50, v50
	s_waitcnt lgkmcnt(0)
	v_lshlrev_b32_e32 v51, 16, v51
	v_mul_f32_e32 v50, v130, v50
	v_mul_f32_e32 v50, v50, v51
	s_nop 1
	v_cvt_pk_bf16_f32 v50, v50, v1
	ds_write_b16 v116, v50
	v_add_f32_e32 v50, v128, v133
	v_mul_f32_e32 v50, 0x3fb8aa3b, v50
	v_exp_f32_e32 v50, v50
	ds_read_u16 v51, v104 offset:37056
	v_rcp_f32_e32 v50, v50
	s_waitcnt lgkmcnt(0)
	v_lshlrev_b32_e32 v51, 16, v51
	v_mul_f32_e32 v50, v130, v50
	v_mul_f32_e32 v50, v50, v51
	s_nop 1
	v_cvt_pk_bf16_f32 v50, v50, v1
	ds_write_b16 v117, v50
	v_add_f32_e32 v50, v129, v133
	v_mul_f32_e32 v50, 0x3fb8aa3b, v50
	v_exp_f32_e32 v50, v50
	ds_read_u16 v51, v104 offset:37328
	v_rcp_f32_e32 v50, v50
	s_waitcnt lgkmcnt(0)
	v_lshlrev_b32_e32 v51, 16, v51
	v_mul_f32_e32 v50, v130, v50
	v_mul_f32_e32 v50, v50, v51
	s_nop 1
	v_cvt_pk_bf16_f32 v50, v50, v1
	ds_write_b16 v118, v50
	v_add_f32_e32 v50, v131, v133
	v_mul_f32_e32 v50, 0x3fb8aa3b, v50
	v_exp_f32_e32 v50, v50
	ds_read_u16 v51, v104 offset:37600
	v_rcp_f32_e32 v50, v50
	s_waitcnt lgkmcnt(0)
	v_lshlrev_b32_e32 v51, 16, v51
	v_mul_f32_e32 v50, v130, v50
	v_mul_f32_e32 v50, v50, v51
	s_nop 1
	v_cvt_pk_bf16_f32 v50, v50, v1
	ds_write_b16 v119, v50
	v_add_f32_e32 v50, v133, v132
	v_mul_f32_e32 v50, 0x3fb8aa3b, v50
	v_exp_f32_e32 v50, v50
	ds_read_u16 v51, v104 offset:37872
	v_rcp_f32_e32 v50, v50
	s_waitcnt lgkmcnt(0)
	v_lshlrev_b32_e32 v51, 16, v51
	v_mul_f32_e32 v50, v130, v50
	v_mul_f32_e32 v50, v50, v51
	s_nop 1
	v_cvt_pk_bf16_f32 v50, v50, v1
	ds_write_b16 v120, v50
	s_cbranch_scc1 .LBB0_423
	v_lshl_add_u64 v[2:3], v[72:73], 0, s[20:21]
	v_lshl_add_u64 v[6:7], v[66:67], 0, s[20:21]
	flat_load_dwordx4 v[2:5], v[2:3]
	s_nop 0
	flat_load_dwordx4 v[6:9], v[6:7]
	v_lshl_add_u64 v[10:11], v[70:71], 0, s[20:21]
	v_lshl_add_u64 v[14:15], v[64:65], 0, s[20:21]
	v_lshl_add_u64 v[12:13], v[68:69], 0, s[20:21]
	v_lshl_add_u64 v[16:17], v[62:63], 0, s[20:21]
	flat_load_ushort v50, v[16:17]
	flat_load_ushort v51, v[12:13]
	s_nop 0
	flat_load_dwordx4 v[10:13], v[10:11]
	s_nop 0
	flat_load_dwordx4 v[14:17], v[14:15]
	s_waitcnt vmcnt(0) lgkmcnt(0)
	v_lshlrev_b32_e32 v60, 16, v50
	v_lshlrev_b32_e32 v61, 16, v51
	s_branch .LBB0_423

; #define LAS __attribute__((address_space(3)))
; __device__ __forceinline__ float logsigmoid_fast(float x) { return fminf(x, 0.f) - __logf(1.0f + __expf(-fabsf(x))); }
; template <int KIND, int MODE>
; __device__ __forceinline__ void scan_unit(Frame& F, int layer, int h, int vhalf, int grp) {
;     ...
;         for (int i = 0; i < 2; ++i) { const int e = tid + 512 * i; *(LAS u32x4*)(VS + (e >> 4) * VST + (e & 15) * 8) = pv[i]; }
;         if (KIND == 0) {
; #pragma unroll
;             for (int i = 0; i < 2; ++i) { const int c = tid + 512 * i, t = c >> 4, dc = (c & 15) * 8; const bf16_t* rp = proj + (size_t)(tb + t) * NP + h * 128 + dc;
;                 if (MODE == 1) *(LAS u32x4*)(QS + t * QST + dc) = pq[i];
;                 *(LAS u32x4*)(KS + t * QST + dc) = pk[i]; }
;             X[tid] = pl0; X[tid + 512] = pl1;
;             __syncthreads();
;             float bc[RPT]; float run = 0.f;
; #pragma unroll
;             for (int i = 0; i < RPT; ++i) { const LAS f32x4* lr = (const LAS f32x4*)(X + (tq * RPT + i) * 16); float z = bl;
; #pragma unroll
;                 for (int r = 0; r < 4; ++r) { const f32x4 l4 = lr[r]; z += l4[0] * wl[4 * r] + l4[1] * wl[4 * r + 1] + l4[2] * wl[4 * r + 2] + l4[3] * wl[4 * r + 3]; }
;                 run += logsigmoid_fast(z) * (1.0f / 16.0f); bc[i] = run; }
;             X[1024 + tq * 128 + d] = run;
.LBB0_558:
	v_add_u32_e32 v58, v113, v117
	ds_write_b128 v58, v[34:37]
	v_add_u32_e32 v58, v113, v118
	ds_write_b128 v58, v[38:41]
	ds_write_b128 v119, v[50:53]
	ds_write_b128 v119, v[54:57] offset:33792
	ds_write_b128 v120, v[42:45]
	ds_write_b128 v120, v[46:49] offset:33792
	ds_write2st64_b32 v111, v89, v90 offset1:8
	s_waitcnt lgkmcnt(0)
	s_barrier
	ds_read_b128 v[180:183], v110
	ds_read_b128 v[184:187], v110 offset:16
	ds_read_b128 v[188:191], v110 offset:32
	ds_read_b128 v[192:195], v110 offset:48
	ds_read_b128 v[196:199], v110 offset:64
	ds_read_b128 v[200:203], v110 offset:80
	ds_read_b128 v[204:207], v110 offset:96
	ds_read_b128 v[208:211], v110 offset:112
	s_waitcnt lgkmcnt(4)
	v_mul_f32_e32 v212, v94, v181
	v_fmac_f32_e32 v212, v91, v180
	v_fmac_f32_e32 v212, v95, v182
	v_fmac_f32_e32 v212, v96, v183
	v_add_f32_e32 v213, v109, v212
	v_mul_f32_e32 v212, v98, v185
	v_fmac_f32_e32 v212, v97, v184
	v_fmac_f32_e32 v212, v99, v186
	v_fmac_f32_e32 v212, v100, v187
	v_add_f32_e32 v213, v213, v212
	v_mul_f32_e32 v212, v102, v189
	v_fmac_f32_e32 v212, v101, v188
	v_fmac_f32_e32 v212, v103, v190
	v_fmac_f32_e32 v212, v104, v191
	v_add_f32_e32 v213, v213, v212
	v_mul_f32_e32 v212, v106, v193
	v_fmac_f32_e32 v212, v105, v192
	v_fmac_f32_e32 v212, v107, v194
	v_fmac_f32_e32 v212, v108, v195
	v_add_f32_e32 v213, v213, v212
	v_min_f32_e32 v214, 0, v213
	v_mul_f32_e64 v213, |v213|, s65
	v_exp_f32_e32 v213, v213
	s_nop 0
	v_add_f32_e32 v213, 1.0, v213
	v_log_f32_e32 v213, v213
	s_nop 0
	v_mul_f32_e32 v212, 0x3f317217, v213
	v_fma_f32 v212, v213, s75, -v212
	v_fmac_f32_e32 v212, 0x3377d1cf, v213
	v_fmac_f32_e32 v212, 0x3f317217, v213
	v_sub_f32_e32 v213, v214, v212
	v_fma_f32 v58, v213, s64, 0
	ds_read_b128 v[180:183], v110 offset:128
	ds_read_b128 v[184:187], v110 offset:144
	ds_read_b128 v[188:191], v110 offset:160
	ds_read_b128 v[192:195], v110 offset:176
	s_waitcnt lgkmcnt(4)
	v_mul_f32_e32 v212, v94, v197
	v_fmac_f32_e32 v212, v91, v196
	v_fmac_f32_e32 v212, v95, v198
	v_fmac_f32_e32 v212, v96, v199
	v_add_f32_e32 v213, v109, v212
	v_mul_f32_e32 v212, v98, v201
	v_fmac_f32_e32 v212, v97, v200
	v_fmac_f32_e32 v212, v99, v202
	v_fmac_f32_e32 v212, v100, v203
	v_add_f32_e32 v213, v213, v212
	v_mul_f32_e32 v212, v102, v205
	v_fmac_f32_e32 v212, v101, v204
	v_fmac_f32_e32 v212, v103, v206
	v_fmac_f32_e32 v212, v104, v207
	v_add_f32_e32 v213, v213, v212
	v_mul_f32_e32 v212, v106, v209
	v_fmac_f32_e32 v212, v105, v208
	v_fmac_f32_e32 v212, v107, v210
	v_fmac_f32_e32 v212, v108, v211
	v_add_f32_e32 v213, v213, v212
	v_min_f32_e32 v214, 0, v213
	v_mul_f32_e64 v213, |v213|, s65
	v_exp_f32_e32 v213, v213
	s_nop 0
	v_add_f32_e32 v213, 1.0, v213
	v_log_f32_e32 v213, v213
	s_nop 0
	v_mul_f32_e32 v212, 0x3f317217, v213
	v_fma_f32 v212, v213, s75, -v212
	v_fmac_f32_e32 v212, 0x3377d1cf, v213
	v_fmac_f32_e32 v212, 0x3f317217, v213
	v_sub_f32_e32 v213, v214, v212
	v_fmamk_f32 v59, v213, 0x3d800000, v58
	ds_read_b128 v[196:199], v110 offset:192
	ds_read_b128 v[200:203], v110 offset:208
	ds_read_b128 v[204:207], v110 offset:224
	ds_read_b128 v[208:211], v110 offset:240
	s_waitcnt lgkmcnt(4)
	v_mul_f32_e32 v212, v94, v181
	v_fmac_f32_e32 v212, v91, v180
	v_fmac_f32_e32 v212, v95, v182
	v_fmac_f32_e32 v212, v96, v183
	v_add_f32_e32 v213, v109, v212
	v_mul_f32_e32 v212, v98, v185
	v_fmac_f32_e32 v212, v97, v184
	v_fmac_f32_e32 v212, v99, v186
	v_fmac_f32_e32 v212, v100, v187
	v_add_f32_e32 v213, v213, v212
	v_mul_f32_e32 v212, v102, v189
	v_fmac_f32_e32 v212, v101, v188
	v_fmac_f32_e32 v212, v103, v190
	v_fmac_f32_e32 v212, v104, v191
	v_add_f32_e32 v213, v213, v212
	v_mul_f32_e32 v212, v106, v193
	v_fmac_f32_e32 v212, v105, v192
	v_fmac_f32_e32 v212, v107, v194
	v_fmac_f32_e32 v212, v108, v195
	v_add_f32_e32 v213, v213, v212
	v_min_f32_e32 v214, 0, v213
	v_mul_f32_e64 v213, |v213|, s65
	v_exp_f32_e32 v213, v213
	s_nop 0
	v_add_f32_e32 v213, 1.0, v213
	v_log_f32_e32 v213, v213
	s_nop 0
	v_mul_f32_e32 v212, 0x3f317217, v213
	v_fma_f32 v212, v213, s75, -v212
	v_fmac_f32_e32 v212, 0x3377d1cf, v213
	v_fmac_f32_e32 v212, 0x3f317217, v213
	v_sub_f32_e32 v213, v214, v212
	v_fmamk_f32 v60, v213, 0x3d800000, v59
	ds_read_b128 v[180:183], v110 offset:256
	ds_read_b128 v[184:187], v110 offset:272
	ds_read_b128 v[188:191], v110 offset:288
	ds_read_b128 v[192:195], v110 offset:304
	s_waitcnt lgkmcnt(4)
	v_mul_f32_e32 v212, v94, v197
	v_fmac_f32_e32 v212, v91, v196
	v_fmac_f32_e32 v212, v95, v198
	v_fmac_f32_e32 v212, v96, v199
	v_add_f32_e32 v213, v109, v212
	v_mul_f32_e32 v212, v98, v201
	v_fmac_f32_e32 v212, v97, v200
	v_fmac_f32_e32 v212, v99, v202
	v_fmac_f32_e32 v212, v100, v203
	v_add_f32_e32 v213, v213, v212
	v_mul_f32_e32 v212, v102, v205
	v_fmac_f32_e32 v212, v101, v204
	v_fmac_f32_e32 v212, v103, v206
	v_fmac_f32_e32 v212, v104, v207
	v_add_f32_e32 v213, v213, v212
	v_mul_f32_e32 v212, v106, v209
	v_fmac_f32_e32 v212, v105, v208
	v_fmac_f32_e32 v212, v107, v210
	v_fmac_f32_e32 v212, v108, v211
	v_add_f32_e32 v213, v213, v212
	v_min_f32_e32 v214, 0, v213
	v_mul_f32_e64 v213, |v213|, s65
	v_exp_f32_e32 v213, v213
	s_nop 0
	v_add_f32_e32 v213, 1.0, v213
	v_log_f32_e32 v213, v213
	s_nop 0
	v_mul_f32_e32 v212, 0x3f317217, v213
	v_fma_f32 v212, v213, s75, -v212
	v_fmac_f32_e32 v212, 0x3377d1cf, v213
	v_fmac_f32_e32 v212, 0x3f317217, v213
	v_sub_f32_e32 v213, v214, v212
	v_fmamk_f32 v61, v213, 0x3d800000, v60
	ds_read_b128 v[196:199], v110 offset:320
	ds_read_b128 v[200:203], v110 offset:336
	ds_read_b128 v[204:207], v110 offset:352
	ds_read_b128 v[208:211], v110 offset:368
	s_waitcnt lgkmcnt(4)
; #define LAS __attribute__((address_space(3)))
; __device__ __forceinline__ float logsigmoid_fast(float x) { return fminf(x, 0.f) - __logf(1.0f + __expf(-fabsf(x))); }
; template <int KIND, int MODE>
; __device__ __forceinline__ void scan_unit(Frame& F, int layer, int h, int vhalf, int grp) {
;     ...
;             for (int i = 0; i < RPT; ++i) { const LAS f32x4* lr = (const LAS f32x4*)(X + (tq * RPT + i) * 16); float z = bl;
; #pragma unroll
;                 for (int r = 0; r < 4; ++r) { const f32x4 l4 = lr[r]; z += l4[0] * wl[4 * r] + l4[1] * wl[4 * r + 1] + l4[2] * wl[4 * r + 2] + l4[3] * wl[4 * r + 3]; }
;                 run += logsigmoid_fast(z) * (1.0f / 16.0f); bc[i] = run; }
	v_mul_f32_e32 v212, v94, v181
	v_fmac_f32_e32 v212, v91, v180
	v_fmac_f32_e32 v212, v95, v182
	v_fmac_f32_e32 v212, v96, v183
	v_add_f32_e32 v213, v109, v212
	v_mul_f32_e32 v212, v98, v185
	v_fmac_f32_e32 v212, v97, v184
	v_fmac_f32_e32 v212, v99, v186
	v_fmac_f32_e32 v212, v100, v187
	v_add_f32_e32 v213, v213, v212
	v_mul_f32_e32 v212, v102, v189
	v_fmac_f32_e32 v212, v101, v188
	v_fmac_f32_e32 v212, v103, v190
	v_fmac_f32_e32 v212, v104, v191
	v_add_f32_e32 v213, v213, v212
	v_mul_f32_e32 v212, v106, v193
	v_fmac_f32_e32 v212, v105, v192
	v_fmac_f32_e32 v212, v107, v194
	v_fmac_f32_e32 v212, v108, v195
	v_add_f32_e32 v213, v213, v212
	v_min_f32_e32 v214, 0, v213
	v_mul_f32_e64 v213, |v213|, s65
	v_exp_f32_e32 v213, v213
	s_nop 0
	v_add_f32_e32 v213, 1.0, v213
	v_log_f32_e32 v213, v213
	s_nop 0
	v_mul_f32_e32 v212, 0x3f317217, v213
	v_fma_f32 v212, v213, s75, -v212
	v_fmac_f32_e32 v212, 0x3377d1cf, v213
	v_fmac_f32_e32 v212, 0x3f317217, v213
	v_sub_f32_e32 v213, v214, v212
	v_fmamk_f32 v62, v213, 0x3d800000, v61
	ds_read_b128 v[180:183], v110 offset:384
	ds_read_b128 v[184:187], v110 offset:400
	ds_read_b128 v[188:191], v110 offset:416
	ds_read_b128 v[192:195], v110 offset:432
	s_waitcnt lgkmcnt(4)
	v_mul_f32_e32 v212, v94, v197
	v_fmac_f32_e32 v212, v91, v196
	v_fmac_f32_e32 v212, v95, v198
	v_fmac_f32_e32 v212, v96, v199
	v_add_f32_e32 v213, v109, v212
	v_mul_f32_e32 v212, v98, v201
	v_fmac_f32_e32 v212, v97, v200
	v_fmac_f32_e32 v212, v99, v202
	v_fmac_f32_e32 v212, v100, v203
	v_add_f32_e32 v213, v213, v212
	v_mul_f32_e32 v212, v102, v205
	v_fmac_f32_e32 v212, v101, v204
	v_fmac_f32_e32 v212, v103, v206
	v_fmac_f32_e32 v212, v104, v207
	v_add_f32_e32 v213, v213, v212
	v_mul_f32_e32 v212, v106, v209
	v_fmac_f32_e32 v212, v105, v208
	v_fmac_f32_e32 v212, v107, v210
	v_fmac_f32_e32 v212, v108, v211
	v_add_f32_e32 v213, v213, v212
	v_min_f32_e32 v214, 0, v213
	v_mul_f32_e64 v213, |v213|, s65
	v_exp_f32_e32 v213, v213
	s_nop 0
	v_add_f32_e32 v213, 1.0, v213
	v_log_f32_e32 v213, v213
	s_nop 0
	v_mul_f32_e32 v212, 0x3f317217, v213
	v_fma_f32 v212, v213, s75, -v212
	v_fmac_f32_e32 v212, 0x3377d1cf, v213
	v_fmac_f32_e32 v212, 0x3f317217, v213
	v_sub_f32_e32 v213, v214, v212
	v_fmamk_f32 v63, v213, 0x3d800000, v62
	ds_read_b128 v[196:199], v110 offset:448
	ds_read_b128 v[200:203], v110 offset:464
	ds_read_b128 v[204:207], v110 offset:480
	ds_read_b128 v[208:211], v110 offset:496
	s_waitcnt lgkmcnt(4)
	v_mul_f32_e32 v212, v94, v181
	v_fmac_f32_e32 v212, v91, v180
	v_fmac_f32_e32 v212, v95, v182
	v_fmac_f32_e32 v212, v96, v183
	v_add_f32_e32 v213, v109, v212
	v_mul_f32_e32 v212, v98, v185
	v_fmac_f32_e32 v212, v97, v184
	v_fmac_f32_e32 v212, v99, v186
	v_fmac_f32_e32 v212, v100, v187
	v_add_f32_e32 v213, v213, v212
	v_mul_f32_e32 v212, v102, v189
	v_fmac_f32_e32 v212, v101, v188
	v_fmac_f32_e32 v212, v103, v190
	v_fmac_f32_e32 v212, v104, v191
	v_add_f32_e32 v213, v213, v212
	v_mul_f32_e32 v212, v106, v193
	v_fmac_f32_e32 v212, v105, v192
	v_fmac_f32_e32 v212, v107, v194
	v_fmac_f32_e32 v212, v108, v195
	v_add_f32_e32 v213, v213, v212
	v_min_f32_e32 v214, 0, v213
	v_mul_f32_e64 v213, |v213|, s65
	v_exp_f32_e32 v213, v213
	s_nop 0
	v_add_f32_e32 v213, 1.0, v213
	v_log_f32_e32 v213, v213
	s_nop 0
	v_mul_f32_e32 v212, 0x3f317217, v213
	v_fma_f32 v212, v213, s75, -v212
	v_fmac_f32_e32 v212, 0x3377d1cf, v213
	v_fmac_f32_e32 v212, 0x3f317217, v213
	v_sub_f32_e32 v213, v214, v212
	v_fmamk_f32 v65, v213, 0x3d800000, v63
	ds_read_b128 v[180:183], v110 offset:512
	ds_read_b128 v[184:187], v110 offset:528
	ds_read_b128 v[188:191], v110 offset:544
	ds_read_b128 v[192:195], v110 offset:560
	s_waitcnt lgkmcnt(4)
	v_mul_f32_e32 v212, v94, v197
	v_fmac_f32_e32 v212, v91, v196
	v_fmac_f32_e32 v212, v95, v198
	v_fmac_f32_e32 v212, v96, v199
	v_add_f32_e32 v213, v109, v212
	v_mul_f32_e32 v212, v98, v201
	v_fmac_f32_e32 v212, v97, v200
	v_fmac_f32_e32 v212, v99, v202
	v_fmac_f32_e32 v212, v100, v203
	v_add_f32_e32 v213, v213, v212
	v_mul_f32_e32 v212, v102, v205
	v_fmac_f32_e32 v212, v101, v204
	v_fmac_f32_e32 v212, v103, v206
	v_fmac_f32_e32 v212, v104, v207
	v_add_f32_e32 v213, v213, v212
	v_mul_f32_e32 v212, v106, v209
	v_fmac_f32_e32 v212, v105, v208
	v_fmac_f32_e32 v212, v107, v210
	v_fmac_f32_e32 v212, v108, v211
	v_add_f32_e32 v213, v213, v212
	v_min_f32_e32 v214, 0, v213
	v_mul_f32_e64 v213, |v213|, s65
	v_exp_f32_e32 v213, v213
	s_nop 0
	v_add_f32_e32 v213, 1.0, v213
	v_log_f32_e32 v213, v213
	s_nop 0
	v_mul_f32_e32 v212, 0x3f317217, v213
	v_fma_f32 v212, v213, s75, -v212
	v_fmac_f32_e32 v212, 0x3377d1cf, v213
	v_fmac_f32_e32 v212, 0x3f317217, v213
	v_sub_f32_e32 v213, v214, v212
	v_fmamk_f32 v67, v213, 0x3d800000, v65
	ds_read_b128 v[196:199], v110 offset:576
	ds_read_b128 v[200:203], v110 offset:592
	ds_read_b128 v[204:207], v110 offset:608
	ds_read_b128 v[208:211], v110 offset:624
	s_waitcnt lgkmcnt(4)
	v_mul_f32_e32 v212, v94, v181
	v_fmac_f32_e32 v212, v91, v180
	v_fmac_f32_e32 v212, v95, v182
	v_fmac_f32_e32 v212, v96, v183
	v_add_f32_e32 v213, v109, v212
	v_mul_f32_e32 v212, v98, v185
	v_fmac_f32_e32 v212, v97, v184
	v_fmac_f32_e32 v212, v99, v186
	v_fmac_f32_e32 v212, v100, v187
	v_add_f32_e32 v213, v213, v212
	v_mul_f32_e32 v212, v102, v189
	v_fmac_f32_e32 v212, v101, v188
	v_fmac_f32_e32 v212, v103, v190
	v_fmac_f32_e32 v212, v104, v191
	v_add_f32_e32 v213, v213, v212
	v_mul_f32_e32 v212, v106, v193
	v_fmac_f32_e32 v212, v105, v192
	v_fmac_f32_e32 v212, v107, v194
	v_fmac_f32_e32 v212, v108, v195
	v_add_f32_e32 v213, v213, v212
	v_min_f32_e32 v214, 0, v213
	v_mul_f32_e64 v213, |v213|, s65
	v_exp_f32_e32 v213, v213
	s_nop 0
	v_add_f32_e32 v213, 1.0, v213
	v_log_f32_e32 v213, v213
	s_nop 0
	v_mul_f32_e32 v212, 0x3f317217, v213
	v_fma_f32 v212, v213, s75, -v212
	v_fmac_f32_e32 v212, 0x3377d1cf, v213
	v_fmac_f32_e32 v212, 0x3f317217, v213
	v_sub_f32_e32 v213, v214, v212
	v_fmamk_f32 v64, v213, 0x3d800000, v67
	ds_read_b128 v[180:183], v110 offset:640
	ds_read_b128 v[184:187], v110 offset:656
	ds_read_b128 v[188:191], v110 offset:672
	ds_read_b128 v[192:195], v110 offset:688
	s_waitcnt lgkmcnt(4)
; #define LAS __attribute__((address_space(3)))
; __device__ __forceinline__ float logsigmoid_fast(float x) { return fminf(x, 0.f) - __logf(1.0f + __expf(-fabsf(x))); }
; template <int KIND, int MODE>
; __device__ __forceinline__ void scan_unit(Frame& F, int layer, int h, int vhalf, int grp) {
;     ...
;             for (int i = 0; i < RPT; ++i) { const LAS f32x4* lr = (const LAS f32x4*)(X + (tq * RPT + i) * 16); float z = bl;
; #pragma unroll
;                 for (int r = 0; r < 4; ++r) { const f32x4 l4 = lr[r]; z += l4[0] * wl[4 * r] + l4[1] * wl[4 * r + 1] + l4[2] * wl[4 * r + 2] + l4[3] * wl[4 * r + 3]; }
;                 run += logsigmoid_fast(z) * (1.0f / 16.0f); bc[i] = run; }
	v_mul_f32_e32 v212, v94, v197
	v_fmac_f32_e32 v212, v91, v196
	v_fmac_f32_e32 v212, v95, v198
	v_fmac_f32_e32 v212, v96, v199
	v_add_f32_e32 v213, v109, v212
	v_mul_f32_e32 v212, v98, v201
	v_fmac_f32_e32 v212, v97, v200
	v_fmac_f32_e32 v212, v99, v202
	v_fmac_f32_e32 v212, v100, v203
	v_add_f32_e32 v213, v213, v212
	v_mul_f32_e32 v212, v102, v205
	v_fmac_f32_e32 v212, v101, v204
	v_fmac_f32_e32 v212, v103, v206
	v_fmac_f32_e32 v212, v104, v207
	v_add_f32_e32 v213, v213, v212
	v_mul_f32_e32 v212, v106, v209
	v_fmac_f32_e32 v212, v105, v208
	v_fmac_f32_e32 v212, v107, v210
	v_fmac_f32_e32 v212, v108, v211
	v_add_f32_e32 v213, v213, v212
	v_min_f32_e32 v214, 0, v213
	v_mul_f32_e64 v213, |v213|, s65
	v_exp_f32_e32 v213, v213
	s_nop 0
	v_add_f32_e32 v213, 1.0, v213
	v_log_f32_e32 v213, v213
	s_nop 0
	v_mul_f32_e32 v212, 0x3f317217, v213
	v_fma_f32 v212, v213, s75, -v212
	v_fmac_f32_e32 v212, 0x3377d1cf, v213
	v_fmac_f32_e32 v212, 0x3f317217, v213
	v_sub_f32_e32 v213, v214, v212
	v_fmamk_f32 v66, v213, 0x3d800000, v64
	ds_read_b128 v[196:199], v110 offset:704
	ds_read_b128 v[200:203], v110 offset:720
	ds_read_b128 v[204:207], v110 offset:736
	ds_read_b128 v[208:211], v110 offset:752
	s_waitcnt lgkmcnt(4)
	v_mul_f32_e32 v212, v94, v181
	v_fmac_f32_e32 v212, v91, v180
	v_fmac_f32_e32 v212, v95, v182
	v_fmac_f32_e32 v212, v96, v183
	v_add_f32_e32 v213, v109, v212
	v_mul_f32_e32 v212, v98, v185
	v_fmac_f32_e32 v212, v97, v184
	v_fmac_f32_e32 v212, v99, v186
	v_fmac_f32_e32 v212, v100, v187
	v_add_f32_e32 v213, v213, v212
	v_mul_f32_e32 v212, v102, v189
	v_fmac_f32_e32 v212, v101, v188
	v_fmac_f32_e32 v212, v103, v190
	v_fmac_f32_e32 v212, v104, v191
	v_add_f32_e32 v213, v213, v212
	v_mul_f32_e32 v212, v106, v193
	v_fmac_f32_e32 v212, v105, v192
	v_fmac_f32_e32 v212, v107, v194
	v_fmac_f32_e32 v212, v108, v195
	v_add_f32_e32 v213, v213, v212
	v_min_f32_e32 v214, 0, v213
	v_mul_f32_e64 v213, |v213|, s65
	v_exp_f32_e32 v213, v213
	s_nop 0
	v_add_f32_e32 v213, 1.0, v213
	v_log_f32_e32 v213, v213
	s_nop 0
	v_mul_f32_e32 v212, 0x3f317217, v213
	v_fma_f32 v212, v213, s75, -v212
	v_fmac_f32_e32 v212, 0x3377d1cf, v213
	v_fmac_f32_e32 v212, 0x3f317217, v213
	v_sub_f32_e32 v213, v214, v212
	v_fmamk_f32 v68, v213, 0x3d800000, v66
	ds_read_b128 v[180:183], v110 offset:768
	ds_read_b128 v[184:187], v110 offset:784
	ds_read_b128 v[188:191], v110 offset:800
	ds_read_b128 v[192:195], v110 offset:816
	s_waitcnt lgkmcnt(4)
	v_mul_f32_e32 v212, v94, v197
	v_fmac_f32_e32 v212, v91, v196
	v_fmac_f32_e32 v212, v95, v198
	v_fmac_f32_e32 v212, v96, v199
	v_add_f32_e32 v213, v109, v212
	v_mul_f32_e32 v212, v98, v201
	v_fmac_f32_e32 v212, v97, v200
	v_fmac_f32_e32 v212, v99, v202
	v_fmac_f32_e32 v212, v100, v203
	v_add_f32_e32 v213, v213, v212
	v_mul_f32_e32 v212, v102, v205
	v_fmac_f32_e32 v212, v101, v204
	v_fmac_f32_e32 v212, v103, v206
	v_fmac_f32_e32 v212, v104, v207
	v_add_f32_e32 v213, v213, v212
	v_mul_f32_e32 v212, v106, v209
	v_fmac_f32_e32 v212, v105, v208
	v_fmac_f32_e32 v212, v107, v210
	v_fmac_f32_e32 v212, v108, v211
	v_add_f32_e32 v213, v213, v212
	v_min_f32_e32 v214, 0, v213
	v_mul_f32_e64 v213, |v213|, s65
	v_exp_f32_e32 v213, v213
	s_nop 0
	v_add_f32_e32 v213, 1.0, v213
	v_log_f32_e32 v213, v213
	s_nop 0
	v_mul_f32_e32 v212, 0x3f317217, v213
	v_fma_f32 v212, v213, s75, -v212
	v_fmac_f32_e32 v212, 0x3377d1cf, v213
	v_fmac_f32_e32 v212, 0x3f317217, v213
	v_sub_f32_e32 v213, v214, v212
	v_fmamk_f32 v69, v213, 0x3d800000, v68
	ds_read_b128 v[196:199], v110 offset:832
	ds_read_b128 v[200:203], v110 offset:848
	ds_read_b128 v[204:207], v110 offset:864
	ds_read_b128 v[208:211], v110 offset:880
	s_waitcnt lgkmcnt(4)
	v_mul_f32_e32 v212, v94, v181
	v_fmac_f32_e32 v212, v91, v180
	v_fmac_f32_e32 v212, v95, v182
	v_fmac_f32_e32 v212, v96, v183
	v_add_f32_e32 v213, v109, v212
	v_mul_f32_e32 v212, v98, v185
	v_fmac_f32_e32 v212, v97, v184
	v_fmac_f32_e32 v212, v99, v186
	v_fmac_f32_e32 v212, v100, v187
	v_add_f32_e32 v213, v213, v212
	v_mul_f32_e32 v212, v102, v189
	v_fmac_f32_e32 v212, v101, v188
	v_fmac_f32_e32 v212, v103, v190
	v_fmac_f32_e32 v212, v104, v191
	v_add_f32_e32 v213, v213, v212
	v_mul_f32_e32 v212, v106, v193
	v_fmac_f32_e32 v212, v105, v192
	v_fmac_f32_e32 v212, v107, v194
	v_fmac_f32_e32 v212, v108, v195
	v_add_f32_e32 v213, v213, v212
	v_min_f32_e32 v214, 0, v213
	v_mul_f32_e64 v213, |v213|, s65
	v_exp_f32_e32 v213, v213
	s_nop 0
	v_add_f32_e32 v213, 1.0, v213
	v_log_f32_e32 v213, v213
	s_nop 0
	v_mul_f32_e32 v212, 0x3f317217, v213
	v_fma_f32 v212, v213, s75, -v212
	v_fmac_f32_e32 v212, 0x3377d1cf, v213
	v_fmac_f32_e32 v212, 0x3f317217, v213
	v_sub_f32_e32 v213, v214, v212
	v_fmamk_f32 v70, v213, 0x3d800000, v69
	ds_read_b128 v[180:183], v110 offset:896
	ds_read_b128 v[184:187], v110 offset:912
	ds_read_b128 v[188:191], v110 offset:928
	ds_read_b128 v[192:195], v110 offset:944
	s_waitcnt lgkmcnt(4)
	v_mul_f32_e32 v212, v94, v197
	v_fmac_f32_e32 v212, v91, v196
	v_fmac_f32_e32 v212, v95, v198
	v_fmac_f32_e32 v212, v96, v199
	v_add_f32_e32 v213, v109, v212
	v_mul_f32_e32 v212, v98, v201
	v_fmac_f32_e32 v212, v97, v200
	v_fmac_f32_e32 v212, v99, v202
	v_fmac_f32_e32 v212, v100, v203
	v_add_f32_e32 v213, v213, v212
	v_mul_f32_e32 v212, v102, v205
	v_fmac_f32_e32 v212, v101, v204
	v_fmac_f32_e32 v212, v103, v206
	v_fmac_f32_e32 v212, v104, v207
	v_add_f32_e32 v213, v213, v212
	v_mul_f32_e32 v212, v106, v209
	v_fmac_f32_e32 v212, v105, v208
	v_fmac_f32_e32 v212, v107, v210
	v_fmac_f32_e32 v212, v108, v211
	v_add_f32_e32 v213, v213, v212
	v_min_f32_e32 v214, 0, v213
	v_mul_f32_e64 v213, |v213|, s65
	v_exp_f32_e32 v213, v213
	s_nop 0
	v_add_f32_e32 v213, 1.0, v213
	v_log_f32_e32 v213, v213
	s_nop 0
	v_mul_f32_e32 v212, 0x3f317217, v213
	v_fma_f32 v212, v213, s75, -v212
	v_fmac_f32_e32 v212, 0x3377d1cf, v213
	v_fmac_f32_e32 v212, 0x3f317217, v213
	v_sub_f32_e32 v213, v214, v212
	v_fmamk_f32 v72, v213, 0x3d800000, v70
	ds_read_b128 v[196:199], v110 offset:960
	ds_read_b128 v[200:203], v110 offset:976
	ds_read_b128 v[204:207], v110 offset:992
	ds_read_b128 v[208:211], v110 offset:1008
	s_waitcnt lgkmcnt(4)
; #define LAS __attribute__((address_space(3)))
; __device__ __forceinline__ unsigned pk2hw(float lo, float hi) { unsigned r; asm("s_nop 1\n\tv_cvt_pk_bf16_f32 %0, %1, %2" : "=v"(r) : "v"(lo), "v"(hi)); return r; }
; __device__ __forceinline__ float logsigmoid_fast(float x) { return fminf(x, 0.f) - __logf(1.0f + __expf(-fabsf(x))); }
; template <int KIND, int MODE>
; __device__ __forceinline__ void scan_unit(Frame& F, int layer, int h, int vhalf, int grp) {
;     ...
;             for (int i = 0; i < RPT; ++i) { const LAS f32x4* lr = (const LAS f32x4*)(X + (tq * RPT + i) * 16); float z = bl;
; #pragma unroll
;                 for (int r = 0; r < 4; ++r) { const f32x4 l4 = lr[r]; z += l4[0] * wl[4 * r] + l4[1] * wl[4 * r + 1] + l4[2] * wl[4 * r + 2] + l4[3] * wl[4 * r + 3]; }
;                 run += logsigmoid_fast(z) * (1.0f / 16.0f); bc[i] = run; }
;             X[1024 + tq * 128 + d] = run;
;             __syncthreads();
;             float pre = 0.f, tot = 0.f;
; #pragma unroll
;             for (int qq = 0; qq < NTQ; ++qq) { const float v = X[1024 + qq * 128 + d]; tot += v; if (qq < tq) pre += v; }
;             const float etot = __expf(tot);
;             if (tq == 0) { X[1536 + d] = etot; gtot += tot; }
; #pragma unroll
;             for (int i = 0; i < RPT; ++i) { const int t = tq * RPT + i; const float bcv = bc[i] + pre;
;                 const float kv = bf2f(KS[t * QST + d]); const float eb = __expf(bcv), ib = __builtin_amdgcn_rcpf(eb);
;                 if (MODE == 1) { const float qv = bf2f(QS[t * QST + d]); const unsigned w0 = pk2hw(qv * 0.08838834764831845f * eb, kv * ib); QS[t * QST + d] = (unsigned short)w0; KS[t * QST + d] = (unsigned short)(w0 >> 16); }
;                 K2[t * QST + d] = (unsigned short)pk2hw(kv * (etot * ib), 0.f); }
	v_mul_f32_e32 v212, v94, v181
	v_fmac_f32_e32 v212, v91, v180
	v_fmac_f32_e32 v212, v95, v182
	v_fmac_f32_e32 v212, v96, v183
	v_add_f32_e32 v213, v109, v212
	v_mul_f32_e32 v212, v98, v185
	v_fmac_f32_e32 v212, v97, v184
	v_fmac_f32_e32 v212, v99, v186
	v_fmac_f32_e32 v212, v100, v187
	v_add_f32_e32 v213, v213, v212
	v_mul_f32_e32 v212, v102, v189
	v_fmac_f32_e32 v212, v101, v188
	v_fmac_f32_e32 v212, v103, v190
	v_fmac_f32_e32 v212, v104, v191
	v_add_f32_e32 v213, v213, v212
	v_mul_f32_e32 v212, v106, v193
	v_fmac_f32_e32 v212, v105, v192
	v_fmac_f32_e32 v212, v107, v194
	v_fmac_f32_e32 v212, v108, v195
	v_add_f32_e32 v213, v213, v212
	v_min_f32_e32 v214, 0, v213
	v_mul_f32_e64 v213, |v213|, s65
	v_exp_f32_e32 v213, v213
	s_nop 0
	v_add_f32_e32 v213, 1.0, v213
	v_log_f32_e32 v213, v213
	s_nop 0
	v_mul_f32_e32 v212, 0x3f317217, v213
	v_fma_f32 v212, v213, s75, -v212
	v_fmac_f32_e32 v212, 0x3377d1cf, v213
	v_fmac_f32_e32 v212, 0x3f317217, v213
	v_sub_f32_e32 v213, v214, v212
	v_fmamk_f32 v73, v213, 0x3d800000, v72
	s_waitcnt lgkmcnt(0)
	v_mul_f32_e32 v212, v94, v197
	v_fmac_f32_e32 v212, v91, v196
	v_fmac_f32_e32 v212, v95, v198
	v_fmac_f32_e32 v212, v96, v199
	v_add_f32_e32 v213, v109, v212
	v_mul_f32_e32 v212, v98, v201
	v_fmac_f32_e32 v212, v97, v200
	v_fmac_f32_e32 v212, v99, v202
	v_fmac_f32_e32 v212, v100, v203
	v_add_f32_e32 v213, v213, v212
	v_mul_f32_e32 v212, v102, v205
	v_fmac_f32_e32 v212, v101, v204
	v_fmac_f32_e32 v212, v103, v206
	v_fmac_f32_e32 v212, v104, v207
	v_add_f32_e32 v213, v213, v212
	v_mul_f32_e32 v212, v106, v209
	v_fmac_f32_e32 v212, v105, v208
	v_fmac_f32_e32 v212, v107, v210
	v_fmac_f32_e32 v212, v108, v211
	v_add_f32_e32 v213, v213, v212
	v_min_f32_e32 v214, 0, v213
	v_mul_f32_e64 v213, |v213|, s65
	v_exp_f32_e32 v213, v213
	s_nop 0
	v_add_f32_e32 v213, 1.0, v213
	v_log_f32_e32 v213, v213
	s_nop 0
	v_mul_f32_e32 v212, 0x3f317217, v213
	v_fma_f32 v212, v213, s75, -v212
	v_fmac_f32_e32 v212, 0x3377d1cf, v213
	v_fmac_f32_e32 v212, 0x3f317217, v213
	v_sub_f32_e32 v213, v214, v212
	v_fmamk_f32 v74, v213, 0x3d800000, v73
	ds_write_b32 v114, v74 offset:4096
	s_waitcnt lgkmcnt(0)
	s_barrier
	ds_read_b32 v71, v121
	ds_read_b32 v76, v122
	ds_read_b32 v77, v123
	ds_read_b32 v78, v124
	s_waitcnt lgkmcnt(0)
	v_add_f32_e32 v75, 0, v71
	s_waitcnt lgkmcnt(2)
	v_add_f32_e32 v71, v75, v76
	s_waitcnt lgkmcnt(1)
	v_add_f32_e32 v71, v71, v77
	s_waitcnt lgkmcnt(0)
	v_add_f32_e32 v71, v71, v78
	v_mul_f32_e32 v71, 0x3fb8aa3b, v71
	v_exp_f32_e32 v71, v71
	s_and_saveexec_b64 s[0:1], s[8:9]
	ds_write_b32 v112, v71 offset:6144
	s_or_b64 exec, exec, s[0:1]
	v_cndmask_b32_e64 v75, 0, v75, s[14:15]
	v_add_f32_e32 v76, v76, v75
	v_cndmask_b32_e64 v75, v75, v76, s[16:17]
	v_add_f32_e32 v76, v77, v75
	v_cndmask_b32_e64 v75, v75, v76, s[18:19]
	v_add_f32_e32 v76, v78, v75
	v_cndmask_b32_e64 v75, v75, v76, s[20:21]
	v_add_f32_e32 v58, v58, v75
	v_mul_f32_e32 v58, 0x3fb8aa3b, v58
	ds_read_u16 v76, v125 offset:33792
	ds_read_u16 v78, v125
	v_exp_f32_e32 v58, v58
	s_cmp_ge_i32 s54, s53
	s_waitcnt lgkmcnt(0)
	v_lshlrev_b32_e32 v76, 16, v76
	v_rcp_f32_e32 v77, v58
	s_waitcnt lgkmcnt(0)
	v_lshlrev_b32_e32 v78, 16, v78
	v_mul_f32_e32 v78, 0x3db504f3, v78
	v_mul_f32_e32 v58, v58, v78
	v_mul_f32_e32 v78, v77, v76
	s_nop 1
	v_cvt_pk_bf16_f32 v58, v58, v78
	ds_write_b16 v125, v58
	ds_write_b16_d16_hi v125, v58 offset:33792
	v_mul_f32_e32 v58, v71, v77
	v_mul_f32_e32 v58, v58, v76
	s_nop 1
	v_cvt_pk_bf16_f32 v58, v58, v1
	ds_write_b16 v126, v58
	v_add_f32_e32 v58, v59, v75
	v_mul_f32_e32 v58, 0x3fb8aa3b, v58
	ds_read_u16 v59, v125 offset:34064
	ds_read_u16 v77, v125 offset:272
	v_exp_f32_e32 v58, v58
	s_waitcnt lgkmcnt(0)
	v_lshlrev_b32_e32 v59, 16, v59
	v_rcp_f32_e32 v76, v58
	s_waitcnt lgkmcnt(0)
	v_lshlrev_b32_e32 v77, 16, v77
	v_mul_f32_e32 v77, 0x3db504f3, v77
	v_mul_f32_e32 v58, v58, v77
	v_mul_f32_e32 v77, v76, v59
	s_nop 1
	v_cvt_pk_bf16_f32 v58, v58, v77
	ds_write_b16 v125, v58 offset:272
	ds_write_b16_d16_hi v125, v58 offset:34064
	v_mul_f32_e32 v58, v71, v76
	v_mul_f32_e32 v58, v58, v59
	s_nop 1
	v_cvt_pk_bf16_f32 v58, v58, v1
	ds_write_b16 v127, v58
	v_add_f32_e32 v58, v60, v75
	v_mul_f32_e32 v58, 0x3fb8aa3b, v58
	ds_read_u16 v59, v125 offset:34336
	ds_read_u16 v76, v125 offset:544
	v_exp_f32_e32 v58, v58
	s_waitcnt lgkmcnt(0)
	v_lshlrev_b32_e32 v59, 16, v59
	v_rcp_f32_e32 v60, v58
	s_waitcnt lgkmcnt(0)
	v_lshlrev_b32_e32 v76, 16, v76
	v_mul_f32_e32 v76, 0x3db504f3, v76
	v_mul_f32_e32 v58, v58, v76
	v_mul_f32_e32 v76, v60, v59
	s_nop 1
	v_cvt_pk_bf16_f32 v58, v58, v76
	ds_write_b16 v125, v58 offset:544
	ds_write_b16_d16_hi v125, v58 offset:34336
	v_mul_f32_e32 v58, v71, v60
	v_mul_f32_e32 v58, v58, v59
	s_nop 1
	v_cvt_pk_bf16_f32 v58, v58, v1
	ds_write_b16 v128, v58
	v_add_f32_e32 v58, v61, v75
	v_mul_f32_e32 v58, 0x3fb8aa3b, v58
	ds_read_u16 v59, v125 offset:34608
	ds_read_u16 v61, v125 offset:816
	v_exp_f32_e32 v58, v58
	s_waitcnt lgkmcnt(0)
	v_lshlrev_b32_e32 v59, 16, v59
	v_rcp_f32_e32 v60, v58
	s_waitcnt lgkmcnt(0)
	v_lshlrev_b32_e32 v61, 16, v61
	v_mul_f32_e32 v61, 0x3db504f3, v61
	v_mul_f32_e32 v58, v58, v61
	v_mul_f32_e32 v61, v60, v59
	s_nop 1
	v_cvt_pk_bf16_f32 v58, v58, v61
	ds_write_b16 v125, v58 offset:816
	ds_write_b16_d16_hi v125, v58 offset:34608
	v_mul_f32_e32 v58, v71, v60
	v_mul_f32_e32 v58, v58, v59
	s_nop 1
	v_cvt_pk_bf16_f32 v58, v58, v1
	ds_write_b16 v129, v58
	v_add_f32_e32 v58, v62, v75
	v_mul_f32_e32 v58, 0x3fb8aa3b, v58
	ds_read_u16 v59, v125 offset:34880
	ds_read_u16 v61, v125 offset:1088
	v_exp_f32_e32 v58, v58
	s_waitcnt lgkmcnt(0)
	v_lshlrev_b32_e32 v59, 16, v59
	v_rcp_f32_e32 v60, v58
	s_waitcnt lgkmcnt(0)
; __device__ __forceinline__ unsigned pk2hw(float lo, float hi) { unsigned r; asm("s_nop 1\n\tv_cvt_pk_bf16_f32 %0, %1, %2" : "=v"(r) : "v"(lo), "v"(hi)); return r; }
; template <int KIND, int MODE>
; __device__ __forceinline__ void scan_unit(Frame& F, int layer, int h, int vhalf, int grp) {
;     ...
;             for (int i = 0; i < RPT; ++i) { const int t = tq * RPT + i; const float bcv = bc[i] + pre;
;                 const float kv = bf2f(KS[t * QST + d]); const float eb = __expf(bcv), ib = __builtin_amdgcn_rcpf(eb);
;                 if (MODE == 1) { const float qv = bf2f(QS[t * QST + d]); const unsigned w0 = pk2hw(qv * 0.08838834764831845f * eb, kv * ib); QS[t * QST + d] = (unsigned short)w0; KS[t * QST + d] = (unsigned short)(w0 >> 16); }
;                 K2[t * QST + d] = (unsigned short)pk2hw(kv * (etot * ib), 0.f); }
	v_lshlrev_b32_e32 v61, 16, v61
	v_mul_f32_e32 v61, 0x3db504f3, v61
	v_mul_f32_e32 v58, v58, v61
	v_mul_f32_e32 v61, v60, v59
	s_nop 1
	v_cvt_pk_bf16_f32 v58, v58, v61
	ds_write_b16 v125, v58 offset:1088
	ds_write_b16_d16_hi v125, v58 offset:34880
	v_mul_f32_e32 v58, v71, v60
	v_mul_f32_e32 v58, v58, v59
	s_nop 1
	v_cvt_pk_bf16_f32 v58, v58, v1
	ds_write_b16 v130, v58
	v_add_f32_e32 v58, v63, v75
	v_mul_f32_e32 v58, 0x3fb8aa3b, v58
	ds_read_u16 v59, v125 offset:35152
	ds_read_u16 v61, v125 offset:1360
	v_exp_f32_e32 v58, v58
	s_waitcnt lgkmcnt(0)
	v_lshlrev_b32_e32 v59, 16, v59
	v_rcp_f32_e32 v60, v58
	s_waitcnt lgkmcnt(0)
	v_lshlrev_b32_e32 v61, 16, v61
	v_mul_f32_e32 v61, 0x3db504f3, v61
	v_mul_f32_e32 v58, v58, v61
	v_mul_f32_e32 v61, v60, v59
	s_nop 1
	v_cvt_pk_bf16_f32 v58, v58, v61
	ds_write_b16 v125, v58 offset:1360
	ds_write_b16_d16_hi v125, v58 offset:35152
	v_mul_f32_e32 v58, v71, v60
	v_mul_f32_e32 v58, v58, v59
	s_nop 1
	v_cvt_pk_bf16_f32 v58, v58, v1
	ds_write_b16 v131, v58
	v_add_f32_e32 v58, v65, v75
	v_mul_f32_e32 v58, 0x3fb8aa3b, v58
	ds_read_u16 v59, v125 offset:35424
	ds_read_u16 v61, v125 offset:1632
	v_exp_f32_e32 v58, v58
	s_waitcnt lgkmcnt(0)
	v_lshlrev_b32_e32 v59, 16, v59
	v_rcp_f32_e32 v60, v58
	s_waitcnt lgkmcnt(0)
	v_lshlrev_b32_e32 v61, 16, v61
	v_mul_f32_e32 v61, 0x3db504f3, v61
	v_mul_f32_e32 v58, v58, v61
	v_mul_f32_e32 v61, v60, v59
	s_nop 1
	v_cvt_pk_bf16_f32 v58, v58, v61
	ds_write_b16 v125, v58 offset:1632
	ds_write_b16_d16_hi v125, v58 offset:35424
	v_mul_f32_e32 v58, v71, v60
	v_mul_f32_e32 v58, v58, v59
	s_nop 1
	v_cvt_pk_bf16_f32 v58, v58, v1
	ds_write_b16 v132, v58
	v_add_f32_e32 v58, v67, v75
	v_mul_f32_e32 v58, 0x3fb8aa3b, v58
	ds_read_u16 v59, v125 offset:35696
	ds_read_u16 v61, v125 offset:1904
	v_exp_f32_e32 v58, v58
	s_waitcnt lgkmcnt(0)
	v_lshlrev_b32_e32 v59, 16, v59
	v_rcp_f32_e32 v60, v58
	s_waitcnt lgkmcnt(0)
	v_lshlrev_b32_e32 v61, 16, v61
	v_mul_f32_e32 v61, 0x3db504f3, v61
	v_mul_f32_e32 v58, v58, v61
	v_mul_f32_e32 v61, v60, v59
	s_nop 1
	v_cvt_pk_bf16_f32 v58, v58, v61
	ds_write_b16 v125, v58 offset:1904
	ds_write_b16_d16_hi v125, v58 offset:35696
	v_mul_f32_e32 v58, v71, v60
	v_mul_f32_e32 v58, v58, v59
	s_nop 1
	v_cvt_pk_bf16_f32 v58, v58, v1
	ds_write_b16 v133, v58
	v_add_f32_e32 v58, v64, v75
	v_mul_f32_e32 v58, 0x3fb8aa3b, v58
	ds_read_u16 v59, v125 offset:35968
	ds_read_u16 v61, v125 offset:2176
	v_exp_f32_e32 v58, v58
	s_waitcnt lgkmcnt(0)
	v_lshlrev_b32_e32 v59, 16, v59
	v_rcp_f32_e32 v60, v58
	s_waitcnt lgkmcnt(0)
	v_lshlrev_b32_e32 v61, 16, v61
	v_mul_f32_e32 v61, 0x3db504f3, v61
	v_mul_f32_e32 v58, v58, v61
	v_mul_f32_e32 v61, v60, v59
	s_nop 1
	v_cvt_pk_bf16_f32 v58, v58, v61
	ds_write_b16 v125, v58 offset:2176
	ds_write_b16_d16_hi v125, v58 offset:35968
	v_mul_f32_e32 v58, v71, v60
	v_mul_f32_e32 v58, v58, v59
	s_nop 1
	v_cvt_pk_bf16_f32 v58, v58, v1
	ds_write_b16 v134, v58
	v_add_f32_e32 v58, v66, v75
	v_mul_f32_e32 v58, 0x3fb8aa3b, v58
	ds_read_u16 v59, v125 offset:36240
	ds_read_u16 v61, v125 offset:2448
	v_exp_f32_e32 v58, v58
	s_waitcnt lgkmcnt(0)
	v_lshlrev_b32_e32 v59, 16, v59
	v_rcp_f32_e32 v60, v58
	s_waitcnt lgkmcnt(0)
	v_lshlrev_b32_e32 v61, 16, v61
	v_mul_f32_e32 v61, 0x3db504f3, v61
	v_mul_f32_e32 v58, v58, v61
	v_mul_f32_e32 v61, v60, v59
	s_nop 1
	v_cvt_pk_bf16_f32 v58, v58, v61
	ds_write_b16 v125, v58 offset:2448
	ds_write_b16_d16_hi v125, v58 offset:36240
	v_mul_f32_e32 v58, v71, v60
	v_mul_f32_e32 v58, v58, v59
	s_nop 1
	v_cvt_pk_bf16_f32 v58, v58, v1
	ds_write_b16 v135, v58
	v_add_f32_e32 v58, v68, v75
	v_mul_f32_e32 v58, 0x3fb8aa3b, v58
	ds_read_u16 v59, v125 offset:36512
	ds_read_u16 v61, v125 offset:2720
	v_exp_f32_e32 v58, v58
	s_waitcnt lgkmcnt(0)
	v_lshlrev_b32_e32 v59, 16, v59
	v_rcp_f32_e32 v60, v58
	s_waitcnt lgkmcnt(0)
	v_lshlrev_b32_e32 v61, 16, v61
	v_mul_f32_e32 v61, 0x3db504f3, v61
	v_mul_f32_e32 v58, v58, v61
	v_mul_f32_e32 v61, v60, v59
	s_nop 1
	v_cvt_pk_bf16_f32 v58, v58, v61
	ds_write_b16 v125, v58 offset:2720
	ds_write_b16_d16_hi v125, v58 offset:36512
	v_mul_f32_e32 v58, v71, v60
	v_mul_f32_e32 v58, v58, v59
	s_nop 1
	v_cvt_pk_bf16_f32 v58, v58, v1
	ds_write_b16 v136, v58
	v_add_f32_e32 v58, v69, v75
	v_mul_f32_e32 v58, 0x3fb8aa3b, v58
	ds_read_u16 v59, v125 offset:36784
	ds_read_u16 v61, v125 offset:2992
	v_exp_f32_e32 v58, v58
	s_waitcnt lgkmcnt(0)
; __device__ __forceinline__ unsigned pk2hw(float lo, float hi) { unsigned r; asm("s_nop 1\n\tv_cvt_pk_bf16_f32 %0, %1, %2" : "=v"(r) : "v"(lo), "v"(hi)); return r; }
; template <int KIND, int MODE>
; __device__ __forceinline__ void scan_unit(Frame& F, int layer, int h, int vhalf, int grp) {
;     ...
;             for (int i = 0; i < RPT; ++i) { const int t = tq * RPT + i; const float bcv = bc[i] + pre;
;                 const float kv = bf2f(KS[t * QST + d]); const float eb = __expf(bcv), ib = __builtin_amdgcn_rcpf(eb);
;                 if (MODE == 1) { const float qv = bf2f(QS[t * QST + d]); const unsigned w0 = pk2hw(qv * 0.08838834764831845f * eb, kv * ib); QS[t * QST + d] = (unsigned short)w0; KS[t * QST + d] = (unsigned short)(w0 >> 16); }
;                 K2[t * QST + d] = (unsigned short)pk2hw(kv * (etot * ib), 0.f); }
;             if (PREF && ch + 1 < (grp + 1) * GC) SCAN_LOAD(tb + 64);
	v_lshlrev_b32_e32 v59, 16, v59
	v_rcp_f32_e32 v60, v58
	s_waitcnt lgkmcnt(0)
	v_lshlrev_b32_e32 v61, 16, v61
	v_mul_f32_e32 v61, 0x3db504f3, v61
	v_mul_f32_e32 v58, v58, v61
	v_mul_f32_e32 v61, v60, v59
	s_nop 1
	v_cvt_pk_bf16_f32 v58, v58, v61
	ds_write_b16 v125, v58 offset:2992
	ds_write_b16_d16_hi v125, v58 offset:36784
	v_mul_f32_e32 v58, v71, v60
	v_mul_f32_e32 v58, v58, v59
	s_nop 1
	v_cvt_pk_bf16_f32 v58, v58, v1
	ds_write_b16 v137, v58
	v_add_f32_e32 v58, v70, v75
	v_mul_f32_e32 v58, 0x3fb8aa3b, v58
	ds_read_u16 v59, v125 offset:37056
	ds_read_u16 v61, v125 offset:3264
	v_exp_f32_e32 v58, v58
	s_waitcnt lgkmcnt(0)
	v_lshlrev_b32_e32 v59, 16, v59
	v_rcp_f32_e32 v60, v58
	s_waitcnt lgkmcnt(0)
	v_lshlrev_b32_e32 v61, 16, v61
	v_mul_f32_e32 v61, 0x3db504f3, v61
	v_mul_f32_e32 v58, v58, v61
	v_mul_f32_e32 v61, v60, v59
	s_nop 1
	v_cvt_pk_bf16_f32 v58, v58, v61
	ds_write_b16 v125, v58 offset:3264
	ds_write_b16_d16_hi v125, v58 offset:37056
	v_mul_f32_e32 v58, v71, v60
	v_mul_f32_e32 v58, v58, v59
	s_nop 1
	v_cvt_pk_bf16_f32 v58, v58, v1
	ds_write_b16 v138, v58
	v_add_f32_e32 v58, v72, v75
	v_mul_f32_e32 v58, 0x3fb8aa3b, v58
	ds_read_u16 v59, v125 offset:37328
	ds_read_u16 v61, v125 offset:3536
	v_exp_f32_e32 v58, v58
	s_waitcnt lgkmcnt(0)
	v_lshlrev_b32_e32 v59, 16, v59
	v_rcp_f32_e32 v60, v58
	s_waitcnt lgkmcnt(0)
	v_lshlrev_b32_e32 v61, 16, v61
	v_mul_f32_e32 v61, 0x3db504f3, v61
	v_mul_f32_e32 v58, v58, v61
	v_mul_f32_e32 v61, v60, v59
	s_nop 1
	v_cvt_pk_bf16_f32 v58, v58, v61
	ds_write_b16 v125, v58 offset:3536
	ds_write_b16_d16_hi v125, v58 offset:37328
	v_mul_f32_e32 v58, v71, v60
	v_mul_f32_e32 v58, v58, v59
	s_nop 1
	v_cvt_pk_bf16_f32 v58, v58, v1
	ds_write_b16 v139, v58
	v_add_f32_e32 v58, v73, v75
	v_mul_f32_e32 v58, 0x3fb8aa3b, v58
	ds_read_u16 v59, v125 offset:37600
	ds_read_u16 v61, v125 offset:3808
	v_exp_f32_e32 v58, v58
	s_waitcnt lgkmcnt(0)
	v_lshlrev_b32_e32 v59, 16, v59
	v_rcp_f32_e32 v60, v58
	s_waitcnt lgkmcnt(0)
	v_lshlrev_b32_e32 v61, 16, v61
	v_mul_f32_e32 v61, 0x3db504f3, v61
	v_mul_f32_e32 v58, v58, v61
	v_mul_f32_e32 v61, v60, v59
	s_nop 1
	v_cvt_pk_bf16_f32 v58, v58, v61
	ds_write_b16 v125, v58 offset:3808
	ds_write_b16_d16_hi v125, v58 offset:37600
	v_mul_f32_e32 v58, v71, v60
	v_mul_f32_e32 v58, v58, v59
	s_nop 1
	v_cvt_pk_bf16_f32 v58, v58, v1
	ds_write_b16 v140, v58
	v_add_f32_e32 v58, v75, v74
	v_mul_f32_e32 v58, 0x3fb8aa3b, v58
	ds_read_u16 v59, v125 offset:37872
	ds_read_u16 v61, v125 offset:4080
	v_exp_f32_e32 v58, v58
	s_waitcnt lgkmcnt(0)
	v_lshlrev_b32_e32 v59, 16, v59
	v_rcp_f32_e32 v60, v58
	s_waitcnt lgkmcnt(0)
	v_lshlrev_b32_e32 v61, 16, v61
	v_mul_f32_e32 v61, 0x3db504f3, v61
	v_mul_f32_e32 v58, v58, v61
	v_mul_f32_e32 v61, v60, v59
	s_nop 1
	v_cvt_pk_bf16_f32 v58, v58, v61
	ds_write_b16 v125, v58 offset:4080
	ds_write_b16_d16_hi v125, v58 offset:37872
	v_mul_f32_e32 v58, v71, v60
	v_mul_f32_e32 v58, v58, v59
	s_nop 1
	v_cvt_pk_bf16_f32 v58, v58, v1
	ds_write_b16 v141, v58
	s_cbranch_scc1 .LBB0_562
	v_add_u32_e32 v56, s52, v148
	v_add_u32_e32 v54, 64, v56
	v_mov_b64_e32 v[52:53], s[60:61]
	v_add_u32_e32 v56, 0x60, v56
	v_mad_i64_i32 v[34:35], s[0:1], v54, s59, v[84:85]
	v_mad_i64_i32 v[50:51], s[0:1], v54, s59, v[86:87]
	v_mad_i64_i32 v[54:55], s[0:1], v54, s59, v[52:53]
	v_mad_i64_i32 v[52:53], s[0:1], v56, s59, v[52:53]
	v_lshl_add_u64 v[52:53], v[52:53], 0, v[0:1]
	v_add_co_u32_e32 v52, vcc, 0x6000, v52
	v_add_u32_e32 v42, s52, v149
	v_lshl_add_u64 v[54:55], v[54:55], 0, v[0:1]
	v_addc_co_u32_e32 v53, vcc, 0, v53, vcc
	v_mad_i64_i32 v[38:39], s[0:1], v42, s59, v[84:85]
	v_mad_i64_i32 v[42:43], s[0:1], v42, s59, v[86:87]
	v_add_co_u32_e32 v54, vcc, 0x6000, v54
	flat_load_dwordx4 v[34:37], v[34:35]
	s_nop 0
	flat_load_dwordx4 v[38:41], v[38:39]
	s_nop 0
	flat_load_dwordx4 v[46:49], v[42:43] offset:1024
	s_nop 0
	flat_load_dwordx4 v[42:45], v[42:43]
	v_addc_co_u32_e32 v55, vcc, 0, v55, vcc
	flat_load_ushort v58, v[52:53]
	flat_load_ushort v59, v[54:55]
	s_nop 0
	flat_load_dwordx4 v[54:57], v[50:51] offset:1024
	s_nop 0
	flat_load_dwordx4 v[50:53], v[50:51]
	s_waitcnt vmcnt(0) lgkmcnt(0)
	v_lshlrev_b32_e32 v90, 16, v58
	v_lshlrev_b32_e32 v89, 16, v59

; __device__ __forceinline__ void final_phase(Frame& F) {
;     const int gw = F.bid * 8 + F.wave, NGW = F.G * 8; const float* ss = WSP(float, OFF_SSP) + (size_t)4 * M * 16; const float* g = INP(I_NORM_FINAL);
;     for (int m = gw; m < M; m += NGW) { const float rs = rsqrtf(row_ss(ss, m) * (1.0f / D) + EPS); f32x4* xr = (f32x4*)(F.out + (size_t)m * D) + F.lane;
; #pragma unroll
;         for (int j = 0; j < 4; ++j) { const f32x4 gg = *((const f32x4*)g + F.lane + 64 * j); xr[64 * j] = xr[64 * j] * rs * gg; } }
; }
.LBB0_1169:
	s_ashr_i32 s0, s0, 6
	v_readlane_b32 s7, v254, 6
	s_add_i32 s6, s0, s7
	s_cmpk_gt_i32 s6, 0x7fff
	s_cbranch_scc1 .LBB0_1172
	s_mov_b32 s2, 0x23ed0
	s_addk_i32 s2, 0x100
	s_ashr_i32 s3, s0, 31
	s_ashr_i32 s5, s7, 31
	v_mov_b32_e32 v1, s2
	s_add_u32 s2, s0, s7
	ds_read_b64 v[2:3], v1
	s_addc_u32 s3, s3, s5
	s_lshl_b64 s[8:9], s[2:3], 12
	s_add_u32 s0, s1, s8
	v_and_b32_e32 v0, 63, v0
	s_addc_u32 s1, s4, s9
	v_readlane_b32 s8, v254, 14
	v_mov_b32_e32 v5, 0
	v_lshlrev_b32_e32 v4, 4, v0
	v_readlane_b32 s9, v254, 15
	s_waitcnt lgkmcnt(0)
	v_lshl_add_u64 v[0:1], v[2:3], 0, v[4:5]
	v_lshl_add_u64 v[2:3], s[0:1], 0, v[4:5]
	s_lshl_b64 s[0:1], s[8:9], 12
	s_lshl_b64 s[2:3], s[2:3], 6
	s_add_u32 s2, s79, s2
	s_addc_u32 s3, s62, s3
	s_add_u32 s2, s2, 0x1f000000
	s_addc_u32 s3, s3, 0
	s_lshl_b64 s[4:5], s[8:9], 6
	v_mov_b32_e32 v4, 0x358637bd
	s_mov_b32 s7, 0x800000
	global_load_dwordx4 v[40:43], v[0:1], off
	global_load_dwordx4 v[44:47], v[0:1], off offset:1024
	global_load_dwordx4 v[48:51], v[0:1], off offset:2048
	global_load_dwordx4 v[52:55], v[0:1], off offset:3072
.LBB0_1171:
	v_mov_b64_e32 v[34:35], s[2:3]
	global_load_dwordx4 v[6:9], v[34:35], off
	global_load_dwordx4 v[10:13], v[34:35], off offset:32
	global_load_dwordx4 v[14:17], v[34:35], off offset:16
	global_load_dwordx4 v[18:21], v[34:35], off offset:48
	global_load_dwordx4 v[22:25], v[2:3], off
	global_load_dwordx4 v[30:33], v[2:3], off offset:1024
	global_load_dwordx4 v[56:59], v[2:3], off offset:2048
	global_load_dwordx4 v[60:63], v[2:3], off offset:3072
	s_add_i32 s6, s6, s8
	s_add_u32 s2, s2, s4
	s_addc_u32 s3, s3, s5
	s_waitcnt vmcnt(0)
	v_mov_b32_e32 v34, v6
	v_mov_b32_e32 v35, v10
	v_mov_b32_e32 v10, v7
	v_mov_b32_e32 v6, v8
	v_mov_b32_e32 v7, v12
	v_mov_b32_e32 v12, v9
	v_mov_b32_e32 v8, v14
	v_mov_b32_e32 v9, v18
	v_mov_b32_e32 v18, v15
	v_mov_b32_e32 v14, v16
	v_mov_b32_e32 v15, v20
	v_mov_b32_e32 v20, v17
	v_pk_add_f32 v[10:11], v[34:35], v[10:11]
	v_pk_add_f32 v[6:7], v[6:7], v[12:13]
	v_pk_add_f32 v[8:9], v[8:9], v[18:19]
	v_pk_add_f32 v[12:13], v[14:15], v[20:21]
	v_pk_add_f32 v[6:7], v[10:11], v[6:7]
	v_pk_add_f32 v[8:9], v[8:9], v[12:13]
	s_nop 0
	v_pk_add_f32 v[6:7], v[6:7], v[8:9]
	s_nop 0
	v_add_f32_e32 v5, v6, v7
	v_fmamk_f32 v5, v5, 0x3a800000, v4
	v_mul_f32_e32 v6, 0x4b800000, v5
	v_cmp_gt_f32_e32 vcc, s7, v5
	s_nop 1
	v_cndmask_b32_e32 v5, v5, v6, vcc
	v_rsq_f32_e32 v5, v5
	s_nop 0
	v_mul_f32_e32 v6, 0x45800000, v5
	v_cndmask_b32_e32 v18, v5, v6, vcc
	v_pk_mul_f32 v[6:7], v[22:23], v[18:19] op_sel_hi:[1,0]
	v_pk_mul_f32 v[8:9], v[24:25], v[18:19] op_sel_hi:[1,0]
	v_pk_mul_f32 v[6:7], v[40:41], v[6:7]
	v_pk_mul_f32 v[8:9], v[42:43], v[8:9]
	global_store_dwordx4 v[2:3], v[6:9], off
	v_pk_mul_f32 v[14:15], v[32:33], v[18:19] op_sel_hi:[1,0]
	v_pk_mul_f32 v[16:17], v[30:31], v[18:19] op_sel_hi:[1,0]
	v_pk_mul_f32 v[12:13], v[46:47], v[14:15]
	v_pk_mul_f32 v[10:11], v[44:45], v[16:17]
	global_store_dwordx4 v[2:3], v[10:13], off offset:1024
	v_pk_mul_f32 v[22:23], v[58:59], v[18:19] op_sel_hi:[1,0]
	v_pk_mul_f32 v[24:25], v[56:57], v[18:19] op_sel_hi:[1,0]
	v_pk_mul_f32 v[28:29], v[50:51], v[22:23]
	v_pk_mul_f32 v[26:27], v[48:49], v[24:25]
	global_store_dwordx4 v[2:3], v[26:29], off offset:2048
	v_pk_mul_f32 v[30:31], v[62:63], v[18:19] op_sel_hi:[1,0]
	v_pk_mul_f32 v[32:33], v[60:61], v[18:19] op_sel_hi:[1,0]
	v_pk_mul_f32 v[38:39], v[54:55], v[30:31]
	v_pk_mul_f32 v[36:37], v[52:53], v[32:33]
	global_store_dwordx4 v[2:3], v[36:39], off offset:3072
	v_lshl_add_u64 v[2:3], v[2:3], 0, s[0:1]
	s_cmp_lt_i32 s6, 0x8000
	s_cbranch_scc1 .LBB0_1171
